# v7 + EpiResid epilogues: flat->global memory ops, all 16 X loads issued up front into free VGPRs, counted vmcnt waits at first consumers
# speedup vs baseline: 1.0064x; 1.0064x over previous
;     __host__ __device__ bool next(int i, Unit& u) const { return StaticOrder::next(i >> 1, u); }
;     __device__ __forceinline__ bool next(int i, Unit& u) const { const int s = i * G + c; if (s >= 128) return false; const int t = s >> 2; u.pm = pm0 + (t & 3); u.pn = t >> 2; u.k0 = (s & 3) * ksub; return true; }
; #define PG8_WAIT_V(n) asm volatile("s_waitcnt vmcnt(" #n ")" ::: "memory")
; template <class Epi, class Sched, bool ALIGN_EPI = false, bool SP2 = false>
; __device__ __forceinline__ void gemm_phase(PG8_LAS unsigned char* lds, const Gemm g, const Sched& S, const Epi& E) {
;     ...
;     for (;;) {
;         const bool has_next = S.next(ui + 1, nxt);
;         const char* nA = has_next ? (const char*)g.A + (size_t)nxt.pm * tsA + (size_t)nxt.k0 * 2 : cA; const char* nB = has_next ? (const char*)g.Bt + (size_t)nxt.pn * tsB + (size_t)nxt.k0 * 2 : cB;
;         for (int t = (DRO && ui > 0) ? 2 : 0; t < nt; t += 2) {
;             const bool last = (t == nt - 2);
;             const char* a1 = cA + (size_t)(t + 1) * kstep;
;             const char* a2 = last ? nA : cA + (size_t)(t + 2) * kstep; const char* b2 = last ? nB : cB + (size_t)(t + 2) * kstep;
;             const char* a3 = a2 + kstep; const char* b3 = b2 + kstep;
;             if (last && has_next) S.a_ready(nxt);
;             if constexpr (SP2) {
;             PG8_TRIP(true, PG8_WAIT_V(8));
.LBB0_932:
	v_add_u32_e32 v0, 0x10000, v186
	v_add_u32_e32 v188, 0x14000, v186
	ds_read_b128 v[112:115], v0
	ds_read_b128 v[120:123], v0 offset:1024
	ds_read_b128 v[124:127], v0 offset:2048
	ds_read_b128 v[128:131], v0 offset:3072
	ds_read_b128 v[148:151], v188
	ds_read_b128 v[152:155], v188 offset:1024
	ds_read_b128 v[156:159], v188 offset:2048
	ds_read_b128 v[160:163], v188 offset:3072
	s_add_u32 s20, s18, 0xfff80080
	s_addc_u32 s21, s19, -1
	s_cmp_eq_u32 s78, 28
	s_cselect_b32 s24, s7, s20
	s_cselect_b32 s25, s6, s21
	s_cselect_b32 s22, s11, s79
	s_cselect_b32 s23, s9, s82
	s_add_u32 s20, s24, 0x80
	s_addc_u32 s21, s25, 0
	ds_read_b128 v[164:167], v187
	ds_read_b128 v[168:171], v187 offset:1024
	ds_read_b128 v[178:181], v187 offset:2048
	ds_read_b128 v[190:193], v187 offset:3072
	ds_read_b128 v[194:197], v187 offset:4096
	ds_read_b128 v[198:201], v187 offset:5120
	ds_read_b128 v[202:205], v187 offset:6144
	ds_read_b128 v[206:209], v187 offset:7168
	s_mov_b32 m0, s57
	s_nop 0
	global_load_lds_dwordx4 v174, s[18:19]
	s_nop 0
	s_mov_b32 m0, s63
	s_nop 0
	global_load_lds_dwordx4 v176, s[18:19]
	s_waitcnt vmcnt(8)
	s_waitcnt lgkmcnt(0)
	s_barrier
	s_setprio 1
	s_waitcnt lgkmcnt(0)
	v_mfma_f32_16x16x32_bf16 v[144:147], v[112:115], v[164:167], v[144:147]
	v_mfma_f32_16x16x32_bf16 v[140:143], v[124:127], v[164:167], v[140:143]
	s_waitcnt lgkmcnt(5)
	v_mfma_f32_16x16x32_bf16 v[116:119], v[112:115], v[178:181], v[116:119]
	v_mfma_f32_16x16x32_bf16 v[108:111], v[124:127], v[178:181], v[108:111]
	s_waitcnt lgkmcnt(3)
	v_mfma_f32_16x16x32_bf16 v[96:99], v[112:115], v[194:197], v[96:99]
	v_mfma_f32_16x16x32_bf16 v[92:95], v[124:127], v[194:197], v[92:95]
	s_waitcnt lgkmcnt(1)
	v_mfma_f32_16x16x32_bf16 v[80:83], v[112:115], v[202:205], v[80:83]
	v_mfma_f32_16x16x32_bf16 v[76:79], v[124:127], v[202:205], v[76:79]
	v_mfma_f32_16x16x32_bf16 v[144:147], v[120:123], v[168:171], v[144:147]
	v_mfma_f32_16x16x32_bf16 v[140:143], v[128:131], v[168:171], v[140:143]
	v_mfma_f32_16x16x32_bf16 v[116:119], v[120:123], v[190:193], v[116:119]
	v_mfma_f32_16x16x32_bf16 v[108:111], v[128:131], v[190:193], v[108:111]
	v_mfma_f32_16x16x32_bf16 v[96:99], v[120:123], v[198:201], v[96:99]
	v_mfma_f32_16x16x32_bf16 v[92:95], v[128:131], v[198:201], v[92:95]
	s_waitcnt lgkmcnt(0)
	v_mfma_f32_16x16x32_bf16 v[80:83], v[120:123], v[206:209], v[80:83]
	v_mfma_f32_16x16x32_bf16 v[76:79], v[128:131], v[206:209], v[76:79]
	s_setprio 0
	s_setprio 1
	v_mfma_f32_16x16x32_bf16 v[136:139], v[148:151], v[164:167], v[136:139]
	v_mfma_f32_16x16x32_bf16 v[132:135], v[156:159], v[164:167], v[132:135]
	v_mfma_f32_16x16x32_bf16 v[104:107], v[148:151], v[178:181], v[104:107]
	v_mfma_f32_16x16x32_bf16 v[100:103], v[156:159], v[178:181], v[100:103]
	v_mfma_f32_16x16x32_bf16 v[88:91], v[148:151], v[194:197], v[88:91]
	v_mfma_f32_16x16x32_bf16 v[84:87], v[156:159], v[194:197], v[84:87]
	v_mfma_f32_16x16x32_bf16 v[72:75], v[148:151], v[202:205], v[72:75]
	v_mfma_f32_16x16x32_bf16 v[68:71], v[156:159], v[202:205], v[68:71]
	v_mfma_f32_16x16x32_bf16 v[136:139], v[152:155], v[168:171], v[136:139]
	v_mfma_f32_16x16x32_bf16 v[132:135], v[160:163], v[168:171], v[132:135]
	v_mfma_f32_16x16x32_bf16 v[104:107], v[152:155], v[190:193], v[104:107]
	v_mfma_f32_16x16x32_bf16 v[100:103], v[160:163], v[190:193], v[100:103]
	v_mfma_f32_16x16x32_bf16 v[88:91], v[152:155], v[198:201], v[88:91]
	v_mfma_f32_16x16x32_bf16 v[84:87], v[160:163], v[198:201], v[84:87]
	v_mfma_f32_16x16x32_bf16 v[72:75], v[152:155], v[206:209], v[72:75]
	v_mfma_f32_16x16x32_bf16 v[68:71], v[160:163], v[206:209], v[68:71]
	s_setprio 0
	s_barrier
	ds_read_b128 v[164:167], v187 offset:16384
	ds_read_b128 v[168:171], v187 offset:17408
	ds_read_b128 v[178:181], v187 offset:18432
	ds_read_b128 v[190:193], v187 offset:19456
	ds_read_b128 v[194:197], v187 offset:20480
	ds_read_b128 v[198:201], v187 offset:21504
	ds_read_b128 v[202:205], v187 offset:22528
	ds_read_b128 v[206:209], v187 offset:23552
	s_mov_b32 m0, s28
	s_nop 0
	global_load_lds_dwordx4 v175, s[22:23]
	s_add_u32 s88, s22, 0x80000
	s_mov_b32 m0, s29
	s_nop 0
	global_load_lds_dwordx4 v177, s[22:23]
	s_addc_u32 s89, s23, 0
	s_mov_b32 m0, s30
	s_nop 0
	global_load_lds_dwordx4 v175, s[88:89]
	s_nop 0
	s_mov_b32 m0, s31
	s_nop 0
	global_load_lds_dwordx4 v177, s[88:89]
	s_nop 0
	s_mov_b32 m0, s27
	s_nop 0
	global_load_lds_dwordx4 v174, s[24:25]
	s_nop 0
	s_mov_b32 m0, s35
	s_nop 0
	global_load_lds_dwordx4 v176, s[24:25]
	s_waitcnt vmcnt(8)
	s_waitcnt lgkmcnt(0)
	s_barrier
	s_setprio 1
	s_waitcnt lgkmcnt(0)
	v_mfma_f32_16x16x32_bf16 v[64:67], v[112:115], v[164:167], v[64:67]
	v_mfma_f32_16x16x32_bf16 v[60:63], v[124:127], v[164:167], v[60:63]
	s_waitcnt lgkmcnt(5)
	v_mfma_f32_16x16x32_bf16 v[48:51], v[112:115], v[178:181], v[48:51]
	v_mfma_f32_16x16x32_bf16 v[44:47], v[124:127], v[178:181], v[44:47]
	s_waitcnt lgkmcnt(3)
	v_mfma_f32_16x16x32_bf16 v[32:35], v[112:115], v[194:197], v[32:35]
	v_mfma_f32_16x16x32_bf16 v[28:31], v[124:127], v[194:197], v[28:31]
	s_waitcnt lgkmcnt(1)
	v_mfma_f32_16x16x32_bf16 v[16:19], v[112:115], v[202:205], v[16:19]
	v_mfma_f32_16x16x32_bf16 v[12:15], v[124:127], v[202:205], v[12:15]
	v_mfma_f32_16x16x32_bf16 v[64:67], v[120:123], v[168:171], v[64:67]
	v_mfma_f32_16x16x32_bf16 v[60:63], v[128:131], v[168:171], v[60:63]
	v_mfma_f32_16x16x32_bf16 v[48:51], v[120:123], v[190:193], v[48:51]
	v_mfma_f32_16x16x32_bf16 v[44:47], v[128:131], v[190:193], v[44:47]
	v_mfma_f32_16x16x32_bf16 v[32:35], v[120:123], v[198:201], v[32:35]
	v_mfma_f32_16x16x32_bf16 v[28:31], v[128:131], v[198:201], v[28:31]
	s_waitcnt lgkmcnt(0)
	v_mfma_f32_16x16x32_bf16 v[16:19], v[120:123], v[206:209], v[16:19]
	v_mfma_f32_16x16x32_bf16 v[12:15], v[128:131], v[206:209], v[12:15]
	s_setprio 0
	s_setprio 1
	v_mfma_f32_16x16x32_bf16 v[56:59], v[148:151], v[164:167], v[56:59]
	v_mfma_f32_16x16x32_bf16 v[52:55], v[156:159], v[164:167], v[52:55]
	v_mfma_f32_16x16x32_bf16 v[40:43], v[148:151], v[178:181], v[40:43]
	v_mfma_f32_16x16x32_bf16 v[36:39], v[156:159], v[178:181], v[36:39]
	v_mfma_f32_16x16x32_bf16 v[24:27], v[148:151], v[194:197], v[24:27]
	v_mfma_f32_16x16x32_bf16 v[20:23], v[156:159], v[194:197], v[20:23]
	v_mfma_f32_16x16x32_bf16 v[8:11], v[148:151], v[202:205], v[8:11]
	v_mfma_f32_16x16x32_bf16 v[2:5], v[156:159], v[202:205], v[4:7]
	v_mfma_f32_16x16x32_bf16 v[56:59], v[152:155], v[168:171], v[56:59]
	v_mfma_f32_16x16x32_bf16 v[52:55], v[160:163], v[168:171], v[52:55]
	v_mfma_f32_16x16x32_bf16 v[40:43], v[152:155], v[190:193], v[40:43]
	v_mfma_f32_16x16x32_bf16 v[36:39], v[160:163], v[190:193], v[36:39]
	v_mfma_f32_16x16x32_bf16 v[24:27], v[152:155], v[198:201], v[24:27]
	v_mfma_f32_16x16x32_bf16 v[20:23], v[160:163], v[198:201], v[20:23]
	v_mfma_f32_16x16x32_bf16 v[8:11], v[152:155], v[206:209], v[8:11]
	v_mfma_f32_16x16x32_bf16 v[2:5], v[160:163], v[206:209], v[2:5]
	s_setprio 0
	s_barrier
	v_add_u32_e32 v189, 0x18000, v186
	v_add_u32_e32 v190, 0x1c000, v186
	ds_read_b128 v[112:115], v189
	ds_read_b128 v[120:123], v189 offset:1024
	ds_read_b128 v[124:127], v189 offset:2048
	ds_read_b128 v[128:131], v189 offset:3072
	ds_read_b128 v[148:151], v190
	ds_read_b128 v[152:155], v190 offset:1024
	ds_read_b128 v[156:159], v190 offset:2048
	ds_read_b128 v[160:163], v190 offset:3072
	ds_read_b128 v[164:167], v187 offset:32768
	ds_read_b128 v[168:171], v187 offset:33792
	ds_read_b128 v[178:181], v187 offset:34816
	ds_read_b128 v[192:195], v187 offset:35840
	ds_read_b128 v[196:199], v187 offset:36864
	ds_read_b128 v[200:203], v187 offset:37888
	ds_read_b128 v[204:207], v187 offset:38912
	ds_read_b128 v[208:211], v187 offset:39936
	s_add_u32 s24, s24, 0x80000
	s_addc_u32 s25, s25, 0
	s_mov_b32 m0, s36
	s_nop 0
	global_load_lds_dwordx4 v174, s[24:25]
	s_nop 0
	s_mov_b32 m0, s37
	s_nop 0
	global_load_lds_dwordx4 v176, s[24:25]
	s_waitcnt vmcnt(8)
	s_waitcnt lgkmcnt(0)
	s_barrier
	s_setprio 1
	s_waitcnt lgkmcnt(0)
	v_mfma_f32_16x16x32_bf16 v[144:147], v[112:115], v[164:167], v[144:147]
	v_mfma_f32_16x16x32_bf16 v[140:143], v[124:127], v[164:167], v[140:143]
	s_waitcnt lgkmcnt(5)
	v_mfma_f32_16x16x32_bf16 v[116:119], v[112:115], v[178:181], v[116:119]
	v_mfma_f32_16x16x32_bf16 v[108:111], v[124:127], v[178:181], v[108:111]
	s_waitcnt lgkmcnt(3)
	v_mfma_f32_16x16x32_bf16 v[96:99], v[112:115], v[196:199], v[96:99]
	v_mfma_f32_16x16x32_bf16 v[92:95], v[124:127], v[196:199], v[92:95]
	s_waitcnt lgkmcnt(1)
	v_mfma_f32_16x16x32_bf16 v[80:83], v[112:115], v[204:207], v[80:83]
	v_mfma_f32_16x16x32_bf16 v[76:79], v[124:127], v[204:207], v[76:79]
	v_mfma_f32_16x16x32_bf16 v[144:147], v[120:123], v[168:171], v[144:147]
	v_mfma_f32_16x16x32_bf16 v[140:143], v[128:131], v[168:171], v[140:143]
	v_mfma_f32_16x16x32_bf16 v[116:119], v[120:123], v[192:195], v[116:119]
	v_mfma_f32_16x16x32_bf16 v[108:111], v[128:131], v[192:195], v[108:111]
	v_mfma_f32_16x16x32_bf16 v[96:99], v[120:123], v[200:203], v[96:99]
	v_mfma_f32_16x16x32_bf16 v[92:95], v[128:131], v[200:203], v[92:95]
	s_waitcnt lgkmcnt(0)
	v_mfma_f32_16x16x32_bf16 v[80:83], v[120:123], v[208:211], v[80:83]
	v_mfma_f32_16x16x32_bf16 v[76:79], v[128:131], v[208:211], v[76:79]
	s_setprio 0
	s_setprio 1
	v_mfma_f32_16x16x32_bf16 v[136:139], v[148:151], v[164:167], v[136:139]
	v_mfma_f32_16x16x32_bf16 v[132:135], v[156:159], v[164:167], v[132:135]
	v_mfma_f32_16x16x32_bf16 v[104:107], v[148:151], v[178:181], v[104:107]
	v_mfma_f32_16x16x32_bf16 v[100:103], v[156:159], v[178:181], v[100:103]
	v_mfma_f32_16x16x32_bf16 v[88:91], v[148:151], v[196:199], v[88:91]
	v_mfma_f32_16x16x32_bf16 v[84:87], v[156:159], v[196:199], v[84:87]
	v_mfma_f32_16x16x32_bf16 v[72:75], v[148:151], v[204:207], v[72:75]
	v_mfma_f32_16x16x32_bf16 v[68:71], v[156:159], v[204:207], v[68:71]
	v_mfma_f32_16x16x32_bf16 v[136:139], v[152:155], v[168:171], v[136:139]
	v_mfma_f32_16x16x32_bf16 v[132:135], v[160:163], v[168:171], v[132:135]
	v_mfma_f32_16x16x32_bf16 v[104:107], v[152:155], v[192:195], v[104:107]
	v_mfma_f32_16x16x32_bf16 v[100:103], v[160:163], v[192:195], v[100:103]
	v_mfma_f32_16x16x32_bf16 v[88:91], v[152:155], v[200:203], v[88:91]
	v_mfma_f32_16x16x32_bf16 v[84:87], v[160:163], v[200:203], v[84:87]
	v_mfma_f32_16x16x32_bf16 v[72:75], v[152:155], v[208:211], v[72:75]
	v_mfma_f32_16x16x32_bf16 v[68:71], v[160:163], v[208:211], v[68:71]
	s_setprio 0
	s_barrier
;     __device__ __forceinline__ void operator()(const f32x4 (&acc)[2][2][4][2], const Unit& u, int wr, int wc, int fr, int fq) const {
;         const int row0 = u.pm * BM + wr * 64 + fr, col0 = u.pn * BM + wc * 32 + 8 * fq;
; template <class Epi, class Sched, bool ALIGN_EPI = false, bool SP2 = false>
; __device__ __forceinline__ void gemm_phase(PG8_LAS unsigned char* lds, const Gemm g, const Sched& S, const Epi& E) {
;     ...
;         for (int t = (DRO && ui > 0) ? 2 : 0; t < nt; t += 2) {
;             const bool last = (t == nt - 2);
;             const char* a1 = cA + (size_t)(t + 1) * kstep;
;             const char* a2 = last ? nA : cA + (size_t)(t + 2) * kstep; const char* b2 = last ? nB : cB + (size_t)(t + 2) * kstep;
;             const char* a3 = a2 + kstep; const char* b3 = b2 + kstep;
;             if (last && has_next) S.a_ready(nxt);
;             if constexpr (SP2) {
;             PG8_TRIP(true, PG8_WAIT_V(8));
;             } else {
;             PG8_LDB(B0, 0, 0); PG8_SCHED; PG8_LDA(At, 0, 0); PG8_STAGE(PG8_SA(1, 1), a1 + hsA, voffA);
;             PG8_WAIT_L(8); PG8_BAR; PG8_WAIT_L(0); PG8_MMA(0, 0, At, B0); PG8_BAR; PG8_SCHED;
;             PG8_LDB(B1, 0, 1); PG8_STAGE(PG8_SB(0, 0), b2, voffB);
;             PG8_BAR; PG8_WAIT_L(0); PG8_MMA(0, 1, At, B1); PG8_BAR;
;             PG8_LDA(At, 0, 1); PG8_STAGE(PG8_SA(0, 0), a2, voffA);
;             PG8_BAR; PG8_WAIT_L(0); PG8_MMA(1, 0, At, B0); PG8_BAR; PG8_SCHED;
;             PG8_STAGE(PG8_SB(0, 1), b2 + hsB, voffB);
;             PG8_WAIT_V(6); PG8_BAR; PG8_MMA(1, 1, At, B1); PG8_BAR;
;             PG8_LDB(B0, 1, 0); PG8_SCHED; PG8_LDA(At, 1, 0); PG8_STAGE(PG8_SA(0, 1), a2 + hsA, voffA);
;             PG8_WAIT_L(8); PG8_BAR; PG8_WAIT_L(0); PG8_MMA(0, 0, At, B0); PG8_BAR; PG8_SCHED;
;             PG8_LDB(B1, 1, 1); PG8_STAGE(PG8_SB(1, 0), b3, voffB);
;             PG8_BAR; PG8_WAIT_L(0); PG8_MMA(0, 1, At, B1); PG8_BAR;
;             PG8_LDA(At, 1, 1); PG8_STAGE(PG8_SA(1, 0), a3, voffA);
;             PG8_BAR; PG8_WAIT_L(0); PG8_MMA(1, 0, At, B0); PG8_BAR; PG8_SCHED;
;             PG8_STAGE(PG8_SB(1, 1), b3 + hsB, voffB);
;             PG8_WAIT_V(6); PG8_BAR; PG8_MMA(1, 1, At, B1); PG8_BAR;
;             }
;         }
;         if constexpr (DRO) { asm volatile("" ::: "memory"); PG8_STAGE(PG8_SA(1, 1), nA + kstep + hsA, voffA); asm volatile("" ::: "memory"); }
	ds_read_b128 v[164:167], v187 offset:49152
	ds_read_b128 v[168:171], v187 offset:50176
	ds_read_b128 v[178:181], v187 offset:51200
	ds_read_b128 v[192:195], v187 offset:52224
	ds_read_b128 v[196:199], v187 offset:53248
	ds_read_b128 v[200:203], v187 offset:54272
	ds_read_b128 v[204:207], v187 offset:55296
	ds_read_b128 v[208:211], v187 offset:56320
	s_add_u32 s24, s22, 0x80
	s_addc_u32 s25, s23, 0
	s_mov_b32 m0, s44
	s_nop 0
	global_load_lds_dwordx4 v175, s[24:25]
	s_add_u32 s22, s22, 0x80080
	s_mov_b32 m0, s48
	s_nop 0
	global_load_lds_dwordx4 v177, s[24:25]
	s_addc_u32 s23, s23, 0
	s_mov_b32 m0, s52
	s_nop 0
	global_load_lds_dwordx4 v175, s[22:23]
	s_nop 0
	s_mov_b32 m0, s53
	s_nop 0
	global_load_lds_dwordx4 v177, s[22:23]
	s_nop 0
	s_mov_b32 m0, s49
	s_nop 0
	global_load_lds_dwordx4 v174, s[20:21]
	s_nop 0
	s_mov_b32 m0, s51
	s_nop 0
	global_load_lds_dwordx4 v176, s[20:21]
	s_waitcnt vmcnt(8)
	s_waitcnt lgkmcnt(0)
	s_barrier
	s_setprio 1
	s_waitcnt lgkmcnt(0)
	v_mfma_f32_16x16x32_bf16 v[64:67], v[112:115], v[164:167], v[64:67]
	v_mfma_f32_16x16x32_bf16 v[60:63], v[124:127], v[164:167], v[60:63]
	s_waitcnt lgkmcnt(5)
	v_mfma_f32_16x16x32_bf16 v[48:51], v[112:115], v[178:181], v[48:51]
	v_mfma_f32_16x16x32_bf16 v[44:47], v[124:127], v[178:181], v[44:47]
	s_waitcnt lgkmcnt(3)
	v_mfma_f32_16x16x32_bf16 v[32:35], v[112:115], v[196:199], v[32:35]
	v_mfma_f32_16x16x32_bf16 v[28:31], v[124:127], v[196:199], v[28:31]
	s_waitcnt lgkmcnt(1)
	v_mfma_f32_16x16x32_bf16 v[16:19], v[112:115], v[204:207], v[16:19]
	v_mfma_f32_16x16x32_bf16 v[12:15], v[124:127], v[204:207], v[12:15]
	v_mfma_f32_16x16x32_bf16 v[64:67], v[120:123], v[168:171], v[64:67]
	v_mfma_f32_16x16x32_bf16 v[60:63], v[128:131], v[168:171], v[60:63]
	v_mfma_f32_16x16x32_bf16 v[48:51], v[120:123], v[192:195], v[48:51]
	v_mfma_f32_16x16x32_bf16 v[44:47], v[128:131], v[192:195], v[44:47]
	v_mfma_f32_16x16x32_bf16 v[32:35], v[120:123], v[200:203], v[32:35]
	v_mfma_f32_16x16x32_bf16 v[28:31], v[128:131], v[200:203], v[28:31]
	s_waitcnt lgkmcnt(0)
	v_mfma_f32_16x16x32_bf16 v[16:19], v[120:123], v[208:211], v[16:19]
	v_mfma_f32_16x16x32_bf16 v[12:15], v[128:131], v[208:211], v[12:15]
	s_setprio 0
	s_setprio 1
	v_mfma_f32_16x16x32_bf16 v[56:59], v[148:151], v[164:167], v[56:59]
	v_mfma_f32_16x16x32_bf16 v[52:55], v[156:159], v[164:167], v[52:55]
	v_mfma_f32_16x16x32_bf16 v[40:43], v[148:151], v[178:181], v[40:43]
	v_mfma_f32_16x16x32_bf16 v[36:39], v[156:159], v[178:181], v[36:39]
	v_mfma_f32_16x16x32_bf16 v[24:27], v[148:151], v[196:199], v[24:27]
	v_mfma_f32_16x16x32_bf16 v[20:23], v[156:159], v[196:199], v[20:23]
	v_mfma_f32_16x16x32_bf16 v[6:9], v[148:151], v[204:207], v[8:11]
	v_mfma_f32_16x16x32_bf16 v[2:5], v[156:159], v[204:207], v[2:5]
	v_mfma_f32_16x16x32_bf16 v[56:59], v[152:155], v[168:171], v[56:59]
	v_mfma_f32_16x16x32_bf16 v[52:55], v[160:163], v[168:171], v[52:55]
	v_mfma_f32_16x16x32_bf16 v[40:43], v[152:155], v[192:195], v[40:43]
	v_mfma_f32_16x16x32_bf16 v[36:39], v[160:163], v[192:195], v[36:39]
	v_mfma_f32_16x16x32_bf16 v[24:27], v[152:155], v[200:203], v[24:27]
	v_mfma_f32_16x16x32_bf16 v[20:23], v[160:163], v[200:203], v[20:23]
	v_mfma_f32_16x16x32_bf16 v[8:11], v[152:155], v[208:211], v[6:9]
	v_mfma_f32_16x16x32_bf16 v[4:7], v[160:163], v[208:211], v[2:5]
	s_setprio 0
	s_barrier
	s_add_i32 s78, s78, 2
	s_add_u32 s79, s79, 0x100
	s_addc_u32 s82, s82, 0
	s_add_u32 s18, s18, 0x100
	s_addc_u32 s19, s19, 0
	s_cmp_gt_u32 s78, 29
	s_cbranch_scc0 .LBB0_932
	s_add_u32 s18, s7, 0x80080
	s_addc_u32 s19, s6, 0
	s_min_i32 s6, s69, 64
	v_lshl_add_u32 v2, s69, 8, v184
	s_ashr_i32 s6, s6, 4
	s_mul_hi_i32 s7, s6, 0xc000
	s_mul_i32 s6, s6, 0xc000
	v_ashrrev_i32_e32 v3, 31, v2
	s_mov_b32 m0, s57
	s_nop 0
	global_load_lds_dwordx4 v174, s[18:19]
	v_lshl_or_b32 v148, s67, 8, v185
	s_add_u32 s6, s40, s6
	v_lshlrev_b64 v[2:3], 12, v[2:3]
	s_mov_b32 m0, s63
	s_nop 0
	global_load_lds_dwordx4 v176, s[18:19]
	s_addc_u32 s7, s41, s7
	v_ashrrev_i32_e32 v149, 31, v148
	v_lshl_add_u64 v[2:3], s[80:81], 0, v[2:3]
	v_lshl_add_u64 v[112:113], v[148:149], 2, s[6:7]
	v_lshl_add_u64 v[2:3], v[148:149], 1, v[2:3]
	global_load_dwordx4 v[128:131], v[112:113], off
	global_load_dwordx4 v[124:127], v[112:113], off offset:16
	global_load_dwordx4 v[120:123], v[112:113], off offset:512
	global_load_dwordx4 v[112:115], v[112:113], off offset:528
	global_load_dwordx4 v[178:181], v[2:3], off
	global_load_dwordx4 v[192:195], v[2:3], off offset:256
	v_add_co_u32_e32 v172, vcc, 0x10000, v2
	s_nop 1
	v_addc_co_u32_e32 v173, vcc, 0, v3, vcc
	global_load_dwordx4 v[196:199], v[172:173], off
	global_load_dwordx4 v[164:167], v[172:173], off offset:256
	v_add_co_u32_e32 v170, vcc, 0x20000, v2
	s_nop 1
	v_addc_co_u32_e32 v171, vcc, 0, v3, vcc
	global_load_dwordx4 v[160:163], v[170:171], off
	global_load_dwordx4 v[156:159], v[170:171], off offset:256
	v_add_co_u32_e32 v168, vcc, 0x30000, v2
	s_nop 1
	v_addc_co_u32_e32 v169, vcc, 0, v3, vcc
	global_load_dwordx4 v[152:155], v[168:169], off
	global_load_dwordx4 v[148:151], v[168:169], off offset:256
	v_add_co_u32_e32 v244, vcc, 0x80000, v2
	s_nop 1
	v_addc_co_u32_e32 v245, vcc, 0, v3, vcc
	global_load_dwordx4 v[212:215], v[244:245], off
	global_load_dwordx4 v[216:219], v[244:245], off offset:256
	v_add_co_u32_e32 v246, vcc, 0x90000, v2
	s_nop 1
	v_addc_co_u32_e32 v247, vcc, 0, v3, vcc
	global_load_dwordx4 v[220:223], v[246:247], off
	global_load_dwordx4 v[224:227], v[246:247], off offset:256
	v_add_co_u32_e32 v248, vcc, 0xa0000, v2
	s_nop 1
	v_addc_co_u32_e32 v249, vcc, 0, v3, vcc
	global_load_dwordx4 v[228:231], v[248:249], off
	global_load_dwordx4 v[232:235], v[248:249], off offset:256
	v_add_co_u32_e32 v250, vcc, 0xb0000, v2
	s_nop 1
	v_addc_co_u32_e32 v251, vcc, 0, v3, vcc
	global_load_dwordx4 v[236:239], v[250:251], off
	global_load_dwordx4 v[240:243], v[250:251], off offset:256
	s_nop 0
	s_nop 0
	s_mov_b32 s6, 0x10000
	s_mov_b32 s6, 0x90000
	s_nop 0
	s_mov_b64 s[18:19], -1
	s_nop 0
	s_waitcnt vmcnt(15)
; #define ER_LOAD(dst, ai, mp) do { _Pragma("unroll") for (int mm = 0; mm < 2; ++mm) _Pragma("unroll") for (int bj = 0; bj < 2; ++bj) \
;             dst[mm][bj] = *(const u32x4*)(xb + (size_t)((ai) * HALF + (2 * (mp) + mm) * 16) * 2048 + bj * HALF); } while (0)
;     __device__ __forceinline__ void operator()(const f32x4 (&acc)[2][2][4][2], const Unit& u, int wr, int wc, int fr, int fq) const {
;     ...
;         ER_LOAD(xa, 0, 0); ER_LOAD(xc, 0, 1);
;         ER_STORE(xa, 0, 0); ER_LOAD(xa, 1, 0);
;         ER_STORE(xc, 0, 1); ER_LOAD(xc, 1, 1);
	v_cvt_f32_f16_e32 v200, v178
	v_cvt_f32_f16_sdwa v201, v178 dst_sel:DWORD dst_unused:UNUSED_PAD src0_sel:WORD_1
	v_cvt_f32_f16_e32 v178, v179
	v_cvt_f32_f16_sdwa v179, v179 dst_sel:DWORD dst_unused:UNUSED_PAD src0_sel:WORD_1
	v_pk_fma_f32 v[144:145], v[144:145], v[128:129], v[200:201]
	v_pk_fma_f32 v[146:147], v[146:147], v[130:131], v[178:179]
	v_cvt_f32_f16_e32 v178, v180
	v_cvt_f32_f16_sdwa v179, v180 dst_sel:DWORD dst_unused:UNUSED_PAD src0_sel:WORD_1
	v_cvt_f32_f16_e32 v180, v181
	v_cvt_f32_f16_sdwa v181, v181 dst_sel:DWORD dst_unused:UNUSED_PAD src0_sel:WORD_1
	v_pk_fma_f32 v[180:181], v[142:143], v[126:127], v[180:181]
	v_pk_fma_f32 v[142:143], v[140:141], v[124:125], v[178:179]
	v_cvt_pk_f16_f32 v140, v144, v145
	v_cvt_pk_f16_f32 v141, v146, v147
	v_cvt_pk_f16_f32 v142, v142, v143
	v_cvt_pk_f16_f32 v143, v180, v181
	global_store_dwordx4 v[2:3], v[140:143], off
	s_nop 1
	s_waitcnt vmcnt(15)
	v_cvt_f32_f16_e32 v140, v192
	v_cvt_f32_f16_sdwa v141, v192 dst_sel:DWORD dst_unused:UNUSED_PAD src0_sel:WORD_1
	v_cvt_f32_f16_e32 v142, v193
	v_cvt_f32_f16_sdwa v143, v193 dst_sel:DWORD dst_unused:UNUSED_PAD src0_sel:WORD_1
	v_pk_fma_f32 v[136:137], v[136:137], v[120:121], v[140:141]
	v_cvt_f32_f16_e32 v140, v194
	v_pk_fma_f32 v[138:139], v[138:139], v[122:123], v[142:143]
	v_cvt_f32_f16_sdwa v141, v194 dst_sel:DWORD dst_unused:UNUSED_PAD src0_sel:WORD_1
	v_cvt_f32_f16_e32 v142, v195
	v_cvt_f32_f16_sdwa v143, v195 dst_sel:DWORD dst_unused:UNUSED_PAD src0_sel:WORD_1
	v_pk_fma_f32 v[142:143], v[134:135], v[114:115], v[142:143]
	v_pk_fma_f32 v[134:135], v[132:133], v[112:113], v[140:141]
	v_cvt_pk_f16_f32 v132, v136, v137
	v_cvt_pk_f16_f32 v133, v138, v139
	v_cvt_pk_f16_f32 v134, v134, v135
	v_cvt_pk_f16_f32 v135, v142, v143
	global_store_dwordx4 v[2:3], v[132:135], off offset:256
	s_waitcnt vmcnt(13)
	v_cvt_f32_f16_e32 v136, v160
	v_cvt_f32_f16_sdwa v137, v160 dst_sel:DWORD dst_unused:UNUSED_PAD src0_sel:WORD_1
	v_cvt_f32_f16_e32 v132, v196
	v_cvt_f32_f16_sdwa v133, v196 dst_sel:DWORD dst_unused:UNUSED_PAD src0_sel:WORD_1
	v_cvt_f32_f16_e32 v134, v197
	v_cvt_f32_f16_sdwa v135, v197 dst_sel:DWORD dst_unused:UNUSED_PAD src0_sel:WORD_1
	v_cvt_f32_f16_e32 v138, v161
	v_pk_fma_f32 v[116:117], v[116:117], v[128:129], v[132:133]
	v_cvt_f32_f16_e32 v132, v198
	v_pk_fma_f32 v[118:119], v[118:119], v[130:131], v[134:135]
	v_cvt_f32_f16_sdwa v133, v198 dst_sel:DWORD dst_unused:UNUSED_PAD src0_sel:WORD_1
	v_cvt_f32_f16_e32 v134, v199
	v_cvt_f32_f16_sdwa v135, v199 dst_sel:DWORD dst_unused:UNUSED_PAD src0_sel:WORD_1
	v_cvt_f32_f16_sdwa v139, v161 dst_sel:DWORD dst_unused:UNUSED_PAD src0_sel:WORD_1
	v_pk_fma_f32 v[96:97], v[96:97], v[128:129], v[136:137]
	v_cvt_f32_f16_e32 v136, v162
	v_pk_fma_f32 v[134:135], v[110:111], v[126:127], v[134:135]
	v_pk_fma_f32 v[110:111], v[108:109], v[124:125], v[132:133]
	v_cvt_pk_f16_f32 v108, v116, v117
	v_cvt_pk_f16_f32 v109, v118, v119
	v_cvt_pk_f16_f32 v110, v110, v111
	v_cvt_pk_f16_f32 v111, v134, v135
	global_store_dwordx4 v[172:173], v[108:111], off
	v_add_co_u32_e32 v134, vcc, s83, v2
	s_nop 0
	v_cvt_f32_f16_e32 v108, v164
	v_cvt_f32_f16_sdwa v109, v164 dst_sel:DWORD dst_unused:UNUSED_PAD src0_sel:WORD_1
	v_cvt_f32_f16_e32 v110, v165
	v_cvt_f32_f16_sdwa v111, v165 dst_sel:DWORD dst_unused:UNUSED_PAD src0_sel:WORD_1
	v_addc_co_u32_e32 v135, vcc, 0, v3, vcc
	v_pk_fma_f32 v[104:105], v[104:105], v[120:121], v[108:109]
	v_pk_fma_f32 v[106:107], v[106:107], v[122:123], v[110:111]
	v_cvt_f32_f16_e32 v108, v166
	v_cvt_f32_f16_sdwa v109, v166 dst_sel:DWORD dst_unused:UNUSED_PAD src0_sel:WORD_1
	v_cvt_f32_f16_e32 v110, v167
	v_cvt_f32_f16_sdwa v111, v167 dst_sel:DWORD dst_unused:UNUSED_PAD src0_sel:WORD_1
	v_pk_fma_f32 v[98:99], v[98:99], v[130:131], v[138:139]
	v_cvt_f32_f16_sdwa v137, v162 dst_sel:DWORD dst_unused:UNUSED_PAD src0_sel:WORD_1
	v_cvt_f32_f16_e32 v138, v163
	v_pk_fma_f32 v[110:111], v[102:103], v[114:115], v[110:111]
	v_pk_fma_f32 v[102:103], v[100:101], v[112:113], v[108:109]
	v_cvt_pk_f16_f32 v100, v104, v105
	v_cvt_pk_f16_f32 v101, v106, v107
	v_cvt_pk_f16_f32 v102, v102, v103
	v_cvt_pk_f16_f32 v103, v110, v111
	global_store_dwordx4 v[172:173], v[100:103], off offset:256
	v_cvt_f32_f16_sdwa v139, v163 dst_sel:DWORD dst_unused:UNUSED_PAD src0_sel:WORD_1
	v_add_co_u32_e32 v132, vcc, s6, v2
	s_mov_b32 s6, 0xa0000
	v_pk_fma_f32 v[138:139], v[94:95], v[126:127], v[138:139]
	v_pk_fma_f32 v[94:95], v[92:93], v[124:125], v[136:137]
	v_addc_co_u32_e32 v133, vcc, 0, v3, vcc
	v_cvt_pk_f16_f32 v92, v96, v97
	v_cvt_pk_f16_f32 v93, v98, v99
	v_cvt_pk_f16_f32 v94, v94, v95
	v_cvt_pk_f16_f32 v95, v138, v139
	s_nop 0
	global_store_dwordx4 v[170:171], v[92:95], off
	s_nop 1
	s_waitcnt vmcnt(15)
	v_cvt_f32_f16_e32 v92, v156
	v_cvt_f32_f16_sdwa v93, v156 dst_sel:DWORD dst_unused:UNUSED_PAD src0_sel:WORD_1
	v_cvt_f32_f16_e32 v94, v157
	v_cvt_f32_f16_sdwa v95, v157 dst_sel:DWORD dst_unused:UNUSED_PAD src0_sel:WORD_1
	v_pk_fma_f32 v[88:89], v[88:89], v[120:121], v[92:93]
	v_cvt_f32_f16_e32 v92, v158
	v_pk_fma_f32 v[90:91], v[90:91], v[122:123], v[94:95]
	v_cvt_f32_f16_sdwa v93, v158 dst_sel:DWORD dst_unused:UNUSED_PAD src0_sel:WORD_1
	v_cvt_f32_f16_e32 v94, v159
	v_cvt_f32_f16_sdwa v95, v159 dst_sel:DWORD dst_unused:UNUSED_PAD src0_sel:WORD_1
	v_pk_fma_f32 v[94:95], v[86:87], v[114:115], v[94:95]
	v_pk_fma_f32 v[86:87], v[84:85], v[112:113], v[92:93]
	v_cvt_pk_f16_f32 v84, v88, v89
	v_cvt_pk_f16_f32 v85, v90, v91
	v_cvt_pk_f16_f32 v86, v86, v87
	v_cvt_pk_f16_f32 v87, v94, v95
	global_store_dwordx4 v[170:171], v[84:87], off offset:256
	s_waitcnt vmcnt(13)
; #define ER_LOAD(dst, ai, mp) do { _Pragma("unroll") for (int mm = 0; mm < 2; ++mm) _Pragma("unroll") for (int bj = 0; bj < 2; ++bj) \
;             dst[mm][bj] = *(const u32x4*)(xb + (size_t)((ai) * HALF + (2 * (mp) + mm) * 16) * 2048 + bj * HALF); } while (0)
;     __device__ __forceinline__ void operator()(const f32x4 (&acc)[2][2][4][2], const Unit& u, int wr, int wc, int fr, int fq) const {
;     ...
;         ER_LOAD(xa, 0, 0); ER_LOAD(xc, 0, 1);
;         ER_STORE(xa, 0, 0); ER_LOAD(xa, 1, 0);
;         ER_STORE(xc, 0, 1); ER_LOAD(xc, 1, 1);
;         ER_STORE(xa, 1, 0); ER_STORE(xc, 1, 1);
	v_cvt_f32_f16_e32 v88, v213
	v_cvt_f32_f16_e32 v84, v152
	v_cvt_f32_f16_sdwa v85, v152 dst_sel:DWORD dst_unused:UNUSED_PAD src0_sel:WORD_1
	v_cvt_f32_f16_e32 v86, v153
	v_cvt_f32_f16_sdwa v87, v153 dst_sel:DWORD dst_unused:UNUSED_PAD src0_sel:WORD_1
	v_cvt_f32_f16_sdwa v89, v213 dst_sel:DWORD dst_unused:UNUSED_PAD src0_sel:WORD_1
	v_pk_fma_f32 v[80:81], v[80:81], v[128:129], v[84:85]
	v_cvt_f32_f16_e32 v84, v154
	v_pk_fma_f32 v[82:83], v[82:83], v[130:131], v[86:87]
	v_cvt_f32_f16_sdwa v85, v154 dst_sel:DWORD dst_unused:UNUSED_PAD src0_sel:WORD_1
	v_cvt_f32_f16_e32 v86, v155
	v_cvt_f32_f16_sdwa v87, v155 dst_sel:DWORD dst_unused:UNUSED_PAD src0_sel:WORD_1
	v_pk_fma_f32 v[66:67], v[66:67], v[130:131], v[88:89]
	v_cvt_f32_f16_e32 v88, v215
	v_cvt_f32_f16_sdwa v89, v215 dst_sel:DWORD dst_unused:UNUSED_PAD src0_sel:WORD_1
	v_pk_fma_f32 v[86:87], v[78:79], v[126:127], v[86:87]
	v_pk_fma_f32 v[78:79], v[76:77], v[124:125], v[84:85]
	v_cvt_pk_f16_f32 v76, v80, v81
	v_cvt_pk_f16_f32 v77, v82, v83
	v_cvt_pk_f16_f32 v78, v78, v79
	v_cvt_pk_f16_f32 v79, v86, v87
	global_store_dwordx4 v[168:169], v[76:79], off
	v_add_co_u32_e32 v84, vcc, s6, v2
	s_nop 0
	v_cvt_f32_f16_e32 v76, v148
	v_cvt_f32_f16_sdwa v77, v148 dst_sel:DWORD dst_unused:UNUSED_PAD src0_sel:WORD_1
	v_cvt_f32_f16_e32 v78, v149
	v_cvt_f32_f16_sdwa v79, v149 dst_sel:DWORD dst_unused:UNUSED_PAD src0_sel:WORD_1
	v_addc_co_u32_e32 v85, vcc, 0, v3, vcc
	v_pk_fma_f32 v[72:73], v[72:73], v[120:121], v[76:77]
	v_pk_fma_f32 v[74:75], v[74:75], v[122:123], v[78:79]
	v_cvt_f32_f16_e32 v76, v150
	v_cvt_f32_f16_sdwa v77, v150 dst_sel:DWORD dst_unused:UNUSED_PAD src0_sel:WORD_1
	v_cvt_f32_f16_e32 v78, v151
	v_cvt_f32_f16_sdwa v79, v151 dst_sel:DWORD dst_unused:UNUSED_PAD src0_sel:WORD_1
	s_mov_b32 s6, 0xb0000
	v_add_co_u32_e32 v2, vcc, s6, v2
	v_pk_fma_f32 v[78:79], v[70:71], v[114:115], v[78:79]
	v_pk_fma_f32 v[70:71], v[68:69], v[112:113], v[76:77]
	v_cvt_pk_f16_f32 v68, v72, v73
	v_cvt_pk_f16_f32 v69, v74, v75
	v_cvt_pk_f16_f32 v70, v70, v71
	v_cvt_pk_f16_f32 v71, v78, v79
	global_store_dwordx4 v[168:169], v[68:71], off offset:256
	v_addc_co_u32_e32 v3, vcc, 0, v3, vcc
	v_cvt_f32_f16_e32 v86, v212
	v_cvt_f32_f16_sdwa v87, v212 dst_sel:DWORD dst_unused:UNUSED_PAD src0_sel:WORD_1
	v_pk_fma_f32 v[88:89], v[62:63], v[126:127], v[88:89]
	s_and_b64 vcc, s[16:17], exec
	v_pk_fma_f32 v[64:65], v[64:65], v[128:129], v[86:87]
	v_cvt_f32_f16_e32 v86, v214
	v_cvt_f32_f16_sdwa v87, v214 dst_sel:DWORD dst_unused:UNUSED_PAD src0_sel:WORD_1
	v_pk_fma_f32 v[62:63], v[60:61], v[124:125], v[86:87]
	v_cvt_pk_f16_f32 v60, v64, v65
	v_cvt_pk_f16_f32 v61, v66, v67
	v_cvt_pk_f16_f32 v62, v62, v63
	v_cvt_pk_f16_f32 v63, v88, v89
	global_store_dwordx4 v[134:135], v[60:63], off
	s_nop 1
	s_waitcnt vmcnt(15)
	v_cvt_f32_f16_e32 v60, v216
	v_cvt_f32_f16_sdwa v61, v216 dst_sel:DWORD dst_unused:UNUSED_PAD src0_sel:WORD_1
	v_cvt_f32_f16_e32 v62, v217
	v_cvt_f32_f16_sdwa v63, v217 dst_sel:DWORD dst_unused:UNUSED_PAD src0_sel:WORD_1
	v_pk_fma_f32 v[56:57], v[56:57], v[120:121], v[60:61]
	v_cvt_f32_f16_e32 v60, v218
	v_pk_fma_f32 v[58:59], v[58:59], v[122:123], v[62:63]
	v_cvt_f32_f16_sdwa v61, v218 dst_sel:DWORD dst_unused:UNUSED_PAD src0_sel:WORD_1
	v_cvt_f32_f16_e32 v62, v219
	v_cvt_f32_f16_sdwa v63, v219 dst_sel:DWORD dst_unused:UNUSED_PAD src0_sel:WORD_1
	v_pk_fma_f32 v[62:63], v[54:55], v[114:115], v[62:63]
	v_pk_fma_f32 v[54:55], v[52:53], v[112:113], v[60:61]
	v_cvt_pk_f16_f32 v52, v56, v57
	v_cvt_pk_f16_f32 v53, v58, v59
	v_cvt_pk_f16_f32 v54, v54, v55
	v_cvt_pk_f16_f32 v55, v62, v63
	global_store_dwordx4 v[134:135], v[52:55], off offset:256
	s_nop 1
	s_waitcnt vmcnt(15)
	v_cvt_f32_f16_e32 v52, v220
	v_cvt_f32_f16_sdwa v53, v220 dst_sel:DWORD dst_unused:UNUSED_PAD src0_sel:WORD_1
	v_cvt_f32_f16_e32 v54, v221
	v_cvt_f32_f16_sdwa v55, v221 dst_sel:DWORD dst_unused:UNUSED_PAD src0_sel:WORD_1
	v_pk_fma_f32 v[48:49], v[48:49], v[128:129], v[52:53]
	v_cvt_f32_f16_e32 v52, v222
	v_pk_fma_f32 v[50:51], v[50:51], v[130:131], v[54:55]
	v_cvt_f32_f16_sdwa v53, v222 dst_sel:DWORD dst_unused:UNUSED_PAD src0_sel:WORD_1
	v_cvt_f32_f16_e32 v54, v223
	v_cvt_f32_f16_sdwa v55, v223 dst_sel:DWORD dst_unused:UNUSED_PAD src0_sel:WORD_1
	v_pk_fma_f32 v[54:55], v[46:47], v[126:127], v[54:55]
	v_pk_fma_f32 v[46:47], v[44:45], v[124:125], v[52:53]
	v_cvt_pk_f16_f32 v44, v48, v49
	v_cvt_pk_f16_f32 v45, v50, v51
	v_cvt_pk_f16_f32 v46, v46, v47
	v_cvt_pk_f16_f32 v47, v54, v55
	global_store_dwordx4 v[132:133], v[44:47], off
	s_nop 1
	s_waitcnt vmcnt(15)
	v_cvt_f32_f16_e32 v44, v224
	v_cvt_f32_f16_sdwa v45, v224 dst_sel:DWORD dst_unused:UNUSED_PAD src0_sel:WORD_1
	v_cvt_f32_f16_e32 v46, v225
	v_cvt_f32_f16_sdwa v47, v225 dst_sel:DWORD dst_unused:UNUSED_PAD src0_sel:WORD_1
	v_pk_fma_f32 v[40:41], v[40:41], v[120:121], v[44:45]
	v_cvt_f32_f16_e32 v44, v226
	v_pk_fma_f32 v[42:43], v[42:43], v[122:123], v[46:47]
	v_cvt_f32_f16_sdwa v45, v226 dst_sel:DWORD dst_unused:UNUSED_PAD src0_sel:WORD_1
	v_cvt_f32_f16_e32 v46, v227
	v_cvt_f32_f16_sdwa v47, v227 dst_sel:DWORD dst_unused:UNUSED_PAD src0_sel:WORD_1
	v_pk_fma_f32 v[46:47], v[38:39], v[114:115], v[46:47]
	v_pk_fma_f32 v[38:39], v[36:37], v[112:113], v[44:45]
	v_cvt_pk_f16_f32 v36, v40, v41
	v_cvt_pk_f16_f32 v37, v42, v43
	v_cvt_pk_f16_f32 v38, v38, v39
	v_cvt_pk_f16_f32 v39, v46, v47
	global_store_dwordx4 v[132:133], v[36:39], off offset:256
	s_nop 0
	s_waitcnt vmcnt(15)
; #define ER_LOAD(dst, ai, mp) do { _Pragma("unroll") for (int mm = 0; mm < 2; ++mm) _Pragma("unroll") for (int bj = 0; bj < 2; ++bj) \
;             dst[mm][bj] = *(const u32x4*)(xb + (size_t)((ai) * HALF + (2 * (mp) + mm) * 16) * 2048 + bj * HALF); } while (0)
;     __device__ __forceinline__ void operator()(const f32x4 (&acc)[2][2][4][2], const Unit& u, int wr, int wc, int fr, int fq) const {
;     ...
;         ER_LOAD(xa, 0, 0); ER_LOAD(xc, 0, 1);
;         ER_STORE(xa, 0, 0); ER_LOAD(xa, 1, 0);
;         ER_STORE(xc, 0, 1); ER_LOAD(xc, 1, 1);
;         ER_STORE(xa, 1, 0); ER_STORE(xc, 1, 1);
	v_cvt_f32_f16_e32 v36, v228
	v_cvt_f32_f16_sdwa v37, v228 dst_sel:DWORD dst_unused:UNUSED_PAD src0_sel:WORD_1
	v_cvt_f32_f16_e32 v38, v229
	v_cvt_f32_f16_sdwa v39, v229 dst_sel:DWORD dst_unused:UNUSED_PAD src0_sel:WORD_1
	v_pk_fma_f32 v[32:33], v[32:33], v[128:129], v[36:37]
	v_cvt_f32_f16_e32 v36, v230
	v_pk_fma_f32 v[34:35], v[34:35], v[130:131], v[38:39]
	v_cvt_f32_f16_sdwa v37, v230 dst_sel:DWORD dst_unused:UNUSED_PAD src0_sel:WORD_1
	v_cvt_f32_f16_e32 v38, v231
	v_cvt_f32_f16_sdwa v39, v231 dst_sel:DWORD dst_unused:UNUSED_PAD src0_sel:WORD_1
	v_pk_fma_f32 v[38:39], v[30:31], v[126:127], v[38:39]
	v_pk_fma_f32 v[30:31], v[28:29], v[124:125], v[36:37]
	v_cvt_pk_f16_f32 v28, v32, v33
	v_cvt_pk_f16_f32 v29, v34, v35
	v_cvt_pk_f16_f32 v30, v30, v31
	v_cvt_pk_f16_f32 v31, v38, v39
	global_store_dwordx4 v[84:85], v[28:31], off
	s_nop 1
	s_waitcnt vmcnt(15)
	v_cvt_f32_f16_e32 v28, v232
	v_cvt_f32_f16_sdwa v29, v232 dst_sel:DWORD dst_unused:UNUSED_PAD src0_sel:WORD_1
	v_cvt_f32_f16_e32 v30, v233
	v_cvt_f32_f16_sdwa v31, v233 dst_sel:DWORD dst_unused:UNUSED_PAD src0_sel:WORD_1
	v_pk_fma_f32 v[24:25], v[24:25], v[120:121], v[28:29]
	v_cvt_f32_f16_e32 v28, v234
	v_pk_fma_f32 v[26:27], v[26:27], v[122:123], v[30:31]
	v_cvt_f32_f16_sdwa v29, v234 dst_sel:DWORD dst_unused:UNUSED_PAD src0_sel:WORD_1
	v_cvt_f32_f16_e32 v30, v235
	v_cvt_f32_f16_sdwa v31, v235 dst_sel:DWORD dst_unused:UNUSED_PAD src0_sel:WORD_1
	v_pk_fma_f32 v[30:31], v[22:23], v[114:115], v[30:31]
	v_pk_fma_f32 v[22:23], v[20:21], v[112:113], v[28:29]
	v_cvt_pk_f16_f32 v20, v24, v25
	v_cvt_pk_f16_f32 v21, v26, v27
	v_cvt_pk_f16_f32 v22, v22, v23
	v_cvt_pk_f16_f32 v23, v30, v31
	global_store_dwordx4 v[84:85], v[20:23], off offset:256
	s_nop 1
	s_waitcnt vmcnt(15)
	v_cvt_f32_f16_e32 v20, v236
	v_cvt_f32_f16_sdwa v21, v236 dst_sel:DWORD dst_unused:UNUSED_PAD src0_sel:WORD_1
	v_cvt_f32_f16_e32 v22, v237
	v_cvt_f32_f16_sdwa v23, v237 dst_sel:DWORD dst_unused:UNUSED_PAD src0_sel:WORD_1
	v_pk_fma_f32 v[16:17], v[16:17], v[128:129], v[20:21]
	v_cvt_f32_f16_e32 v20, v238
	v_pk_fma_f32 v[18:19], v[18:19], v[130:131], v[22:23]
	v_cvt_f32_f16_sdwa v21, v238 dst_sel:DWORD dst_unused:UNUSED_PAD src0_sel:WORD_1
	v_cvt_f32_f16_e32 v22, v239
	v_cvt_f32_f16_sdwa v23, v239 dst_sel:DWORD dst_unused:UNUSED_PAD src0_sel:WORD_1
	v_pk_fma_f32 v[22:23], v[14:15], v[126:127], v[22:23]
	v_pk_fma_f32 v[14:15], v[12:13], v[124:125], v[20:21]
	v_cvt_pk_f16_f32 v12, v16, v17
	v_cvt_pk_f16_f32 v13, v18, v19
	v_cvt_pk_f16_f32 v14, v14, v15
	v_cvt_pk_f16_f32 v15, v22, v23
	global_store_dwordx4 v[2:3], v[12:15], off
	s_nop 1
	s_waitcnt vmcnt(15)
	v_cvt_f32_f16_e32 v12, v240
	v_cvt_f32_f16_sdwa v13, v240 dst_sel:DWORD dst_unused:UNUSED_PAD src0_sel:WORD_1
	v_cvt_f32_f16_e32 v14, v241
	v_cvt_f32_f16_sdwa v15, v241 dst_sel:DWORD dst_unused:UNUSED_PAD src0_sel:WORD_1
	v_pk_fma_f32 v[8:9], v[8:9], v[120:121], v[12:13]
	v_cvt_f32_f16_e32 v12, v242
	v_pk_fma_f32 v[10:11], v[10:11], v[122:123], v[14:15]
	v_cvt_f32_f16_sdwa v13, v242 dst_sel:DWORD dst_unused:UNUSED_PAD src0_sel:WORD_1
	v_cvt_f32_f16_e32 v14, v243
	v_cvt_f32_f16_sdwa v15, v243 dst_sel:DWORD dst_unused:UNUSED_PAD src0_sel:WORD_1
	v_pk_fma_f32 v[14:15], v[6:7], v[114:115], v[14:15]
	v_pk_fma_f32 v[6:7], v[4:5], v[112:113], v[12:13]
	v_cvt_pk_f16_f32 v4, v8, v9
	v_cvt_pk_f16_f32 v5, v10, v11
	v_cvt_pk_f16_f32 v6, v6, v7
	v_cvt_pk_f16_f32 v7, v14, v15
	global_store_dwordx4 v[2:3], v[4:7], off offset:256
	s_cbranch_vccz .LBB0_919
	ds_read_b128 v[2:5], v0
	ds_read_b128 v[6:9], v0 offset:1024
	ds_read_b128 v[10:13], v0 offset:2048
	ds_read_b128 v[14:17], v0 offset:3072
	ds_read_b128 v[18:21], v188
	ds_read_b128 v[22:25], v188 offset:1024
	ds_read_b128 v[26:29], v188 offset:2048
	ds_read_b128 v[30:33], v188 offset:3072
	s_add_u32 s18, s12, 0x100
	s_addc_u32 s19, s13, 0
	s_add_u32 s16, s12, 0x180
	s_addc_u32 s17, s13, 0
	s_add_u32 s6, s14, 0x100
	s_addc_u32 s7, s15, 0
	ds_read_b128 v[34:37], v187
	ds_read_b128 v[38:41], v187 offset:1024
	ds_read_b128 v[42:45], v187 offset:2048
	ds_read_b128 v[46:49], v187 offset:3072
	ds_read_b128 v[50:53], v187 offset:4096
	ds_read_b128 v[54:57], v187 offset:5120
	ds_read_b128 v[58:61], v187 offset:6144
	ds_read_b128 v[62:65], v187 offset:7168
	s_waitcnt vmcnt(44)
	s_waitcnt lgkmcnt(0)
	s_barrier
	s_setprio 1
	s_waitcnt lgkmcnt(0)
	v_mfma_f32_16x16x32_bf16 v[90:93], v[2:5], v[58:61], 0
	v_mfma_f32_16x16x32_bf16 v[66:69], v[2:5], v[34:37], 0
	v_mfma_f32_16x16x32_bf16 v[70:73], v[10:13], v[34:37], 0
	v_mfma_f32_16x16x32_bf16 v[74:77], v[2:5], v[42:45], 0
	v_mfma_f32_16x16x32_bf16 v[78:81], v[10:13], v[42:45], 0
	v_mfma_f32_16x16x32_bf16 v[82:85], v[2:5], v[50:53], 0
	v_mfma_f32_16x16x32_bf16 v[86:89], v[10:13], v[50:53], 0
	v_mfma_f32_16x16x32_bf16 v[100:103], v[6:9], v[62:65], v[90:93]
	v_mfma_f32_16x16x32_bf16 v[90:93], v[10:13], v[58:61], 0
	v_mfma_f32_16x16x32_bf16 v[66:69], v[6:9], v[38:41], v[66:69]
	v_mfma_f32_16x16x32_bf16 v[70:73], v[14:17], v[38:41], v[70:73]
	v_mfma_f32_16x16x32_bf16 v[74:77], v[6:9], v[46:49], v[74:77]
	v_mfma_f32_16x16x32_bf16 v[78:81], v[14:17], v[46:49], v[78:81]
	v_mfma_f32_16x16x32_bf16 v[82:85], v[6:9], v[54:57], v[82:85]
	v_mfma_f32_16x16x32_bf16 v[86:89], v[14:17], v[54:57], v[86:89]
	v_mfma_f32_16x16x32_bf16 v[104:107], v[14:17], v[62:65], v[90:93]
	s_setprio 0
	s_setprio 1
	v_mfma_f32_16x16x32_bf16 v[90:93], v[18:21], v[34:37], 0
	v_mfma_f32_16x16x32_bf16 v[34:37], v[26:29], v[34:37], 0
	v_mfma_f32_16x16x32_bf16 v[112:115], v[22:25], v[38:41], v[90:93]
	v_mfma_f32_16x16x32_bf16 v[34:37], v[30:33], v[38:41], v[34:37]
	v_mfma_f32_16x16x32_bf16 v[38:41], v[18:21], v[42:45], 0
	v_mfma_f32_16x16x32_bf16 v[42:45], v[26:29], v[42:45], 0
	v_mfma_f32_16x16x32_bf16 v[38:41], v[22:25], v[46:49], v[38:41]
	v_mfma_f32_16x16x32_bf16 v[42:45], v[30:33], v[46:49], v[42:45]
	v_mfma_f32_16x16x32_bf16 v[46:49], v[18:21], v[50:53], 0
	v_mfma_f32_16x16x32_bf16 v[50:53], v[26:29], v[50:53], 0
	v_mfma_f32_16x16x32_bf16 v[46:49], v[22:25], v[54:57], v[46:49]
	v_mfma_f32_16x16x32_bf16 v[50:53], v[30:33], v[54:57], v[50:53]
	v_mfma_f32_16x16x32_bf16 v[54:57], v[18:21], v[58:61], 0
	v_mfma_f32_16x16x32_bf16 v[58:61], v[26:29], v[58:61], 0
	v_mfma_f32_16x16x32_bf16 v[54:57], v[22:25], v[62:65], v[54:57]
	v_mfma_f32_16x16x32_bf16 v[58:61], v[30:33], v[62:65], v[58:61]
	s_setprio 0
	s_barrier
	ds_read_b128 v[62:65], v187 offset:16384
	ds_read_b128 v[90:93], v187 offset:17408
	ds_read_b128 v[94:97], v187 offset:18432
	ds_read_b128 v[108:111], v187 offset:19456
	ds_read_b128 v[116:119], v187 offset:20480
	ds_read_b128 v[120:123], v187 offset:21504
	ds_read_b128 v[124:127], v187 offset:22528
	ds_read_b128 v[128:131], v187 offset:23552
	s_mov_b32 m0, s28
	s_nop 0
	global_load_lds_dwordx4 v175, s[6:7]
	s_nop 0
	s_mov_b32 m0, s29
	s_nop 0
	global_load_lds_dwordx4 v177, s[6:7]
	s_add_u32 s6, s14, 0x80100
	s_addc_u32 s7, s15, 0
	s_mov_b32 m0, s30
	s_nop 0
	global_load_lds_dwordx4 v175, s[6:7]
	s_nop 0
	s_mov_b32 m0, s31
	s_nop 0
	global_load_lds_dwordx4 v177, s[6:7]
	s_nop 0
	s_mov_b32 m0, s27
	s_nop 0
	global_load_lds_dwordx4 v174, s[18:19]
	s_nop 0
	s_mov_b32 m0, s35
	s_nop 0
	global_load_lds_dwordx4 v176, s[18:19]
	s_waitcnt vmcnt(44)
	s_waitcnt lgkmcnt(0)
	s_barrier
	s_setprio 1
	s_waitcnt lgkmcnt(0)
	v_mfma_f32_16x16x32_bf16 v[132:135], v[2:5], v[62:65], 0
	v_mfma_f32_16x16x32_bf16 v[148:151], v[6:9], v[90:93], v[132:135]
	v_mfma_f32_16x16x32_bf16 v[132:135], v[10:13], v[62:65], 0
	v_mfma_f32_16x16x32_bf16 v[152:155], v[14:17], v[90:93], v[132:135]
	v_mfma_f32_16x16x32_bf16 v[132:135], v[2:5], v[94:97], 0
	v_mfma_f32_16x16x32_bf16 v[156:159], v[6:9], v[108:111], v[132:135]
	v_mfma_f32_16x16x32_bf16 v[132:135], v[10:13], v[94:97], 0
	v_mfma_f32_16x16x32_bf16 v[160:163], v[14:17], v[108:111], v[132:135]
	v_mfma_f32_16x16x32_bf16 v[132:135], v[2:5], v[116:119], 0
	v_mfma_f32_16x16x32_bf16 v[2:5], v[2:5], v[124:127], 0
	v_mfma_f32_16x16x32_bf16 v[164:167], v[6:9], v[120:123], v[132:135]
	v_mfma_f32_16x16x32_bf16 v[2:5], v[6:9], v[128:131], v[2:5]
	v_mfma_f32_16x16x32_bf16 v[6:9], v[10:13], v[124:127], 0
	v_mfma_f32_16x16x32_bf16 v[132:135], v[10:13], v[116:119], 0
	v_mfma_f32_16x16x32_bf16 v[6:9], v[14:17], v[128:131], v[6:9]
	v_mfma_f32_16x16x32_bf16 v[168:171], v[14:17], v[120:123], v[132:135]
	s_setprio 0
	s_setprio 1
	v_mfma_f32_16x16x32_bf16 v[10:13], v[18:21], v[62:65], 0
	v_mfma_f32_16x16x32_bf16 v[178:181], v[22:25], v[90:93], v[10:13]
	v_mfma_f32_16x16x32_bf16 v[10:13], v[26:29], v[62:65], 0
	v_mfma_f32_16x16x32_bf16 v[192:195], v[30:33], v[90:93], v[10:13]
	v_mfma_f32_16x16x32_bf16 v[10:13], v[18:21], v[94:97], 0
	v_mfma_f32_16x16x32_bf16 v[196:199], v[22:25], v[108:111], v[10:13]
	v_mfma_f32_16x16x32_bf16 v[10:13], v[26:29], v[94:97], 0
	v_mfma_f32_16x16x32_bf16 v[200:203], v[30:33], v[108:111], v[10:13]
	v_mfma_f32_16x16x32_bf16 v[10:13], v[18:21], v[116:119], 0
	v_mfma_f32_16x16x32_bf16 v[204:207], v[22:25], v[120:123], v[10:13]
	v_mfma_f32_16x16x32_bf16 v[10:13], v[26:29], v[116:119], 0
	v_mfma_f32_16x16x32_bf16 v[120:123], v[30:33], v[120:123], v[10:13]
	v_mfma_f32_16x16x32_bf16 v[10:13], v[18:21], v[124:127], 0
	v_mfma_f32_16x16x32_bf16 v[208:211], v[22:25], v[128:131], v[10:13]
	v_mfma_f32_16x16x32_bf16 v[10:13], v[26:29], v[124:127], 0
	v_mfma_f32_16x16x32_bf16 v[124:127], v[30:33], v[128:131], v[10:13]
	s_setprio 0
	s_barrier
	s_nop 4
	ds_read_b128 v[10:13], v189
	ds_read_b128 v[14:17], v189 offset:1024
	ds_read_b128 v[20:23], v189 offset:2048
	ds_read_b128 v[24:27], v189 offset:3072
	ds_read_b128 v[128:131], v190
	ds_read_b128 v[212:215], v190 offset:1024
	ds_read_b128 v[216:219], v190 offset:2048
	ds_read_b128 v[188:191], v190 offset:3072
	ds_read_b128 v[28:31], v187 offset:32768
	ds_read_b128 v[62:65], v187 offset:33792
	ds_read_b128 v[220:223], v187 offset:34816
	ds_read_b128 v[224:227], v187 offset:35840
	ds_read_b128 v[228:231], v187 offset:36864
	ds_read_b128 v[232:235], v187 offset:37888
	ds_read_b128 v[236:239], v187 offset:38912
	ds_read_b128 v[240:243], v187 offset:39936
	s_add_u32 s6, s12, 0x80100
	s_addc_u32 s7, s13, 0
	s_mov_b32 m0, s36
	s_nop 0
	global_load_lds_dwordx4 v174, s[6:7]
	s_nop 0
	s_mov_b32 m0, s37
	s_nop 0
	global_load_lds_dwordx4 v176, s[6:7]
	s_waitcnt vmcnt(44)
	s_waitcnt lgkmcnt(0)
	s_barrier
	s_setprio 1
	s_waitcnt lgkmcnt(0)
	v_mfma_f32_16x16x32_bf16 v[66:69], v[10:13], v[28:31], v[66:69]
	v_mfma_f32_16x16x32_bf16 v[144:147], v[14:17], v[62:65], v[66:69]
	v_mfma_f32_16x16x32_bf16 v[66:69], v[20:23], v[28:31], v[70:73]
	v_mfma_f32_16x16x32_bf16 v[140:143], v[24:27], v[62:65], v[66:69]
	v_mfma_f32_16x16x32_bf16 v[66:69], v[10:13], v[220:223], v[74:77]
	v_mfma_f32_16x16x32_bf16 v[116:119], v[14:17], v[224:227], v[66:69]
	v_mfma_f32_16x16x32_bf16 v[66:69], v[20:23], v[220:223], v[78:81]
	v_mfma_f32_16x16x32_bf16 v[108:111], v[24:27], v[224:227], v[66:69]
	v_mfma_f32_16x16x32_bf16 v[66:69], v[10:13], v[228:231], v[82:85]
	v_mfma_f32_16x16x32_bf16 v[96:99], v[14:17], v[232:235], v[66:69]
	v_mfma_f32_16x16x32_bf16 v[66:69], v[20:23], v[228:231], v[86:89]
	v_mfma_f32_16x16x32_bf16 v[92:95], v[24:27], v[232:235], v[66:69]
	v_mfma_f32_16x16x32_bf16 v[66:69], v[10:13], v[236:239], v[100:103]
	v_mfma_f32_16x16x32_bf16 v[80:83], v[14:17], v[240:243], v[66:69]
	v_mfma_f32_16x16x32_bf16 v[66:69], v[20:23], v[236:239], v[104:107]
	v_mfma_f32_16x16x32_bf16 v[76:79], v[24:27], v[240:243], v[66:69]
	s_setprio 0
	s_setprio 1
	v_mfma_f32_16x16x32_bf16 v[66:69], v[128:131], v[28:31], v[112:115]
	v_mfma_f32_16x16x32_bf16 v[28:31], v[216:219], v[28:31], v[34:37]
	v_mfma_f32_16x16x32_bf16 v[132:135], v[188:191], v[62:65], v[28:31]
	v_mfma_f32_16x16x32_bf16 v[28:31], v[128:131], v[220:223], v[38:41]
	v_mfma_f32_16x16x32_bf16 v[104:107], v[212:215], v[224:227], v[28:31]
	v_mfma_f32_16x16x32_bf16 v[28:31], v[216:219], v[220:223], v[42:45]
	v_mfma_f32_16x16x32_bf16 v[100:103], v[188:191], v[224:227], v[28:31]
	v_mfma_f32_16x16x32_bf16 v[28:31], v[128:131], v[228:231], v[46:49]
	v_mfma_f32_16x16x32_bf16 v[88:91], v[212:215], v[232:235], v[28:31]
	v_mfma_f32_16x16x32_bf16 v[28:31], v[216:219], v[228:231], v[50:53]
	v_mfma_f32_16x16x32_bf16 v[84:87], v[188:191], v[232:235], v[28:31]
	v_mfma_f32_16x16x32_bf16 v[28:31], v[128:131], v[236:239], v[54:57]
	v_mfma_f32_16x16x32_bf16 v[72:75], v[212:215], v[240:243], v[28:31]
	v_mfma_f32_16x16x32_bf16 v[28:31], v[216:219], v[236:239], v[58:61]
	v_mfma_f32_16x16x32_bf16 v[136:139], v[212:215], v[62:65], v[66:69]
	v_mfma_f32_16x16x32_bf16 v[68:71], v[188:191], v[240:243], v[28:31]
	s_setprio 0
	s_barrier
	ds_read_b128 v[36:39], v187 offset:49152
	ds_read_b128 v[40:43], v187 offset:50176
	ds_read_b128 v[112:115], v187 offset:51200
	ds_read_b128 v[220:223], v187 offset:52224
	ds_read_b128 v[224:227], v187 offset:53248
	ds_read_b128 v[228:231], v187 offset:54272
	ds_read_b128 v[232:235], v187 offset:55296
	ds_read_b128 v[236:239], v187 offset:56320
	s_add_u32 s6, s14, 0x180
	s_addc_u32 s7, s15, 0
	s_mov_b32 m0, s44
	s_nop 0
	global_load_lds_dwordx4 v175, s[6:7]
	s_nop 0
	s_mov_b32 m0, s48
	s_nop 0
	global_load_lds_dwordx4 v177, s[6:7]
	s_add_u32 s6, s14, 0x80180
	s_addc_u32 s7, s15, 0
	s_mov_b32 m0, s52
	s_nop 0
	global_load_lds_dwordx4 v175, s[6:7]
	s_nop 0
	s_mov_b32 m0, s53
	s_nop 0
	global_load_lds_dwordx4 v177, s[6:7]
	s_nop 0
	s_mov_b32 m0, s49
	s_nop 0
	global_load_lds_dwordx4 v174, s[16:17]
	s_nop 0
	s_mov_b32 m0, s51
	s_nop 0
	global_load_lds_dwordx4 v176, s[16:17]
	s_waitcnt vmcnt(8)
	s_waitcnt lgkmcnt(0)
	s_barrier
	s_setprio 1
	s_waitcnt lgkmcnt(0)
	v_mfma_f32_16x16x32_bf16 v[28:31], v[10:13], v[36:39], v[148:151]
	v_mfma_f32_16x16x32_bf16 v[64:67], v[14:17], v[40:43], v[28:31]
	v_mfma_f32_16x16x32_bf16 v[28:31], v[20:23], v[36:39], v[152:155]
	v_mfma_f32_16x16x32_bf16 v[60:63], v[24:27], v[40:43], v[28:31]
	v_mfma_f32_16x16x32_bf16 v[28:31], v[10:13], v[112:115], v[156:159]
	v_mfma_f32_16x16x32_bf16 v[48:51], v[14:17], v[220:223], v[28:31]
	v_mfma_f32_16x16x32_bf16 v[28:31], v[20:23], v[112:115], v[160:163]
	v_mfma_f32_16x16x32_bf16 v[44:47], v[24:27], v[220:223], v[28:31]
	v_mfma_f32_16x16x32_bf16 v[28:31], v[10:13], v[224:227], v[164:167]
	v_mfma_f32_16x16x32_bf16 v[2:5], v[10:13], v[232:235], v[2:5]
	v_mfma_f32_16x16x32_bf16 v[32:35], v[14:17], v[228:231], v[28:31]
	v_mfma_f32_16x16x32_bf16 v[28:31], v[20:23], v[224:227], v[168:171]
	v_mfma_f32_16x16x32_bf16 v[16:19], v[14:17], v[236:239], v[2:5]
	v_mfma_f32_16x16x32_bf16 v[2:5], v[20:23], v[232:235], v[6:9]
	v_mfma_f32_16x16x32_bf16 v[28:31], v[24:27], v[228:231], v[28:31]
	v_mfma_f32_16x16x32_bf16 v[12:15], v[24:27], v[236:239], v[2:5]
	s_setprio 0
	s_setprio 1
	v_mfma_f32_16x16x32_bf16 v[2:5], v[128:131], v[36:39], v[178:181]
	v_mfma_f32_16x16x32_bf16 v[56:59], v[212:215], v[40:43], v[2:5]
	v_mfma_f32_16x16x32_bf16 v[2:5], v[216:219], v[36:39], v[192:195]
	v_mfma_f32_16x16x32_bf16 v[52:55], v[188:191], v[40:43], v[2:5]
	v_mfma_f32_16x16x32_bf16 v[2:5], v[128:131], v[112:115], v[196:199]
	v_mfma_f32_16x16x32_bf16 v[40:43], v[212:215], v[220:223], v[2:5]
	v_mfma_f32_16x16x32_bf16 v[2:5], v[216:219], v[112:115], v[200:203]
	v_mfma_f32_16x16x32_bf16 v[36:39], v[188:191], v[220:223], v[2:5]
	v_mfma_f32_16x16x32_bf16 v[2:5], v[128:131], v[224:227], v[204:207]
	v_mfma_f32_16x16x32_bf16 v[24:27], v[212:215], v[228:231], v[2:5]
	v_mfma_f32_16x16x32_bf16 v[2:5], v[216:219], v[224:227], v[120:123]
	v_mfma_f32_16x16x32_bf16 v[20:23], v[188:191], v[228:231], v[2:5]
	v_mfma_f32_16x16x32_bf16 v[2:5], v[128:131], v[232:235], v[208:211]
	v_mfma_f32_16x16x32_bf16 v[8:11], v[212:215], v[236:239], v[2:5]
	v_mfma_f32_16x16x32_bf16 v[2:5], v[216:219], v[232:235], v[124:127]
	v_mfma_f32_16x16x32_bf16 v[4:7], v[188:191], v[236:239], v[2:5]
	s_setprio 0
	s_barrier
	s_mov_b64 s[18:19], 0
	s_branch .LBB0_919

;     __host__ __device__ bool next(int i, Unit& u) const { return StaticOrder::next(i >> 1, u); }
;     __device__ __forceinline__ bool next(int i, Unit& u) const { const int s = i * G + c; if (s >= 128) return false; const int t = s >> 2; u.pm = pm0 + (t & 3); u.pn = t >> 2; u.k0 = (s & 3) * ksub; return true; }
; #define PG8_WAIT_V(n) asm volatile("s_waitcnt vmcnt(" #n ")" ::: "memory")
; template <class Epi, class Sched, bool ALIGN_EPI = false, bool SP2 = false>
; __device__ __forceinline__ void gemm_phase(PG8_LAS unsigned char* lds, const Gemm g, const Sched& S, const Epi& E) {
;     ...
;     for (;;) {
;         const bool has_next = S.next(ui + 1, nxt);
;         const char* nA = has_next ? (const char*)g.A + (size_t)nxt.pm * tsA + (size_t)nxt.k0 * 2 : cA; const char* nB = has_next ? (const char*)g.Bt + (size_t)nxt.pn * tsB + (size_t)nxt.k0 * 2 : cB;
;         for (int t = (DRO && ui > 0) ? 2 : 0; t < nt; t += 2) {
;             const bool last = (t == nt - 2);
;             const char* a1 = cA + (size_t)(t + 1) * kstep;
;             const char* a2 = last ? nA : cA + (size_t)(t + 2) * kstep; const char* b2 = last ? nB : cB + (size_t)(t + 2) * kstep;
;             const char* a3 = a2 + kstep; const char* b3 = b2 + kstep;
;             if (last && has_next) S.a_ready(nxt);
;             if constexpr (SP2) {
;             PG8_TRIP(true, PG8_WAIT_V(8));
.LBB0_1226:
	v_add_u32_e32 v0, 0x10000, v186
	v_add_u32_e32 v188, 0x14000, v186
	ds_read_b128 v[112:115], v0
	ds_read_b128 v[120:123], v0 offset:1024
	ds_read_b128 v[124:127], v0 offset:2048
	ds_read_b128 v[132:135], v0 offset:3072
	ds_read_b128 v[148:151], v188
	ds_read_b128 v[152:155], v188 offset:1024
	ds_read_b128 v[156:159], v188 offset:2048
	ds_read_b128 v[160:163], v188 offset:3072
	s_add_u32 s14, s12, 0xffea0080
	s_addc_u32 s15, s13, -1
	s_cmpk_eq_i32 s52, 0x54
	s_cselect_b32 s18, s8, s14
	s_cselect_b32 s19, s9, s15
	s_cselect_b32 s16, s6, s53
	s_cselect_b32 s17, s7, s57
	s_add_u32 s14, s18, 0x80
	s_addc_u32 s15, s19, 0
	ds_read_b128 v[164:167], v187
	ds_read_b128 v[168:171], v187 offset:1024
	ds_read_b128 v[178:181], v187 offset:2048
	ds_read_b128 v[190:193], v187 offset:3072
	ds_read_b128 v[194:197], v187 offset:4096
	ds_read_b128 v[198:201], v187 offset:5120
	ds_read_b128 v[202:205], v187 offset:6144
	ds_read_b128 v[206:209], v187 offset:7168
	s_mov_b32 m0, s44
	s_nop 0
	global_load_lds_dwordx4 v174, s[12:13]
	s_nop 0
	s_mov_b32 m0, s45
	s_nop 0
	global_load_lds_dwordx4 v176, s[12:13]
	s_waitcnt vmcnt(8)
	s_waitcnt lgkmcnt(0)
	s_barrier
	s_setprio 1
	s_waitcnt lgkmcnt(0)
	v_mfma_f32_16x16x32_bf16 v[144:147], v[112:115], v[164:167], v[144:147]
	v_mfma_f32_16x16x32_bf16 v[140:143], v[124:127], v[164:167], v[140:143]
	s_waitcnt lgkmcnt(5)
	v_mfma_f32_16x16x32_bf16 v[116:119], v[112:115], v[178:181], v[116:119]
	v_mfma_f32_16x16x32_bf16 v[108:111], v[124:127], v[178:181], v[108:111]
	s_waitcnt lgkmcnt(3)
	v_mfma_f32_16x16x32_bf16 v[96:99], v[112:115], v[194:197], v[96:99]
	v_mfma_f32_16x16x32_bf16 v[92:95], v[124:127], v[194:197], v[92:95]
	s_waitcnt lgkmcnt(1)
	v_mfma_f32_16x16x32_bf16 v[80:83], v[112:115], v[202:205], v[80:83]
	v_mfma_f32_16x16x32_bf16 v[76:79], v[124:127], v[202:205], v[76:79]
	v_mfma_f32_16x16x32_bf16 v[144:147], v[120:123], v[168:171], v[144:147]
	v_mfma_f32_16x16x32_bf16 v[140:143], v[132:135], v[168:171], v[140:143]
	v_mfma_f32_16x16x32_bf16 v[116:119], v[120:123], v[190:193], v[116:119]
	v_mfma_f32_16x16x32_bf16 v[108:111], v[132:135], v[190:193], v[108:111]
	v_mfma_f32_16x16x32_bf16 v[96:99], v[120:123], v[198:201], v[96:99]
	v_mfma_f32_16x16x32_bf16 v[92:95], v[132:135], v[198:201], v[92:95]
	s_waitcnt lgkmcnt(0)
	v_mfma_f32_16x16x32_bf16 v[80:83], v[120:123], v[206:209], v[80:83]
	v_mfma_f32_16x16x32_bf16 v[76:79], v[132:135], v[206:209], v[76:79]
	s_setprio 0
	s_setprio 1
	v_mfma_f32_16x16x32_bf16 v[136:139], v[148:151], v[164:167], v[136:139]
	v_mfma_f32_16x16x32_bf16 v[128:131], v[156:159], v[164:167], v[128:131]
	v_mfma_f32_16x16x32_bf16 v[104:107], v[148:151], v[178:181], v[104:107]
	v_mfma_f32_16x16x32_bf16 v[100:103], v[156:159], v[178:181], v[100:103]
	v_mfma_f32_16x16x32_bf16 v[88:91], v[148:151], v[194:197], v[88:91]
	v_mfma_f32_16x16x32_bf16 v[84:87], v[156:159], v[194:197], v[84:87]
	v_mfma_f32_16x16x32_bf16 v[72:75], v[148:151], v[202:205], v[72:75]
	v_mfma_f32_16x16x32_bf16 v[68:71], v[156:159], v[202:205], v[68:71]
	v_mfma_f32_16x16x32_bf16 v[136:139], v[152:155], v[168:171], v[136:139]
	v_mfma_f32_16x16x32_bf16 v[128:131], v[160:163], v[168:171], v[128:131]
	v_mfma_f32_16x16x32_bf16 v[104:107], v[152:155], v[190:193], v[104:107]
	v_mfma_f32_16x16x32_bf16 v[100:103], v[160:163], v[190:193], v[100:103]
	v_mfma_f32_16x16x32_bf16 v[88:91], v[152:155], v[198:201], v[88:91]
	v_mfma_f32_16x16x32_bf16 v[84:87], v[160:163], v[198:201], v[84:87]
	v_mfma_f32_16x16x32_bf16 v[72:75], v[152:155], v[206:209], v[72:75]
	v_mfma_f32_16x16x32_bf16 v[68:71], v[160:163], v[206:209], v[68:71]
	s_setprio 0
	s_barrier
	ds_read_b128 v[164:167], v187 offset:16384
	ds_read_b128 v[168:171], v187 offset:17408
	ds_read_b128 v[178:181], v187 offset:18432
	ds_read_b128 v[190:193], v187 offset:19456
	ds_read_b128 v[194:197], v187 offset:20480
	ds_read_b128 v[198:201], v187 offset:21504
	ds_read_b128 v[202:205], v187 offset:22528
	ds_read_b128 v[206:209], v187 offset:23552
	s_mov_b32 m0, s22
	s_nop 0
	global_load_lds_dwordx4 v175, s[16:17]
	s_add_u32 s78, s16, 0x160000
	s_mov_b32 m0, s23
	s_nop 0
	global_load_lds_dwordx4 v177, s[16:17]
	s_addc_u32 s79, s17, 0
	s_mov_b32 m0, s26
	s_nop 0
	global_load_lds_dwordx4 v175, s[78:79]
	s_nop 0
	s_mov_b32 m0, s27
	s_nop 0
	global_load_lds_dwordx4 v177, s[78:79]
	s_nop 0
	s_mov_b32 m0, s21
	s_nop 0
	global_load_lds_dwordx4 v174, s[18:19]
	s_nop 0
	s_mov_b32 m0, s28
	s_nop 0
	global_load_lds_dwordx4 v176, s[18:19]
	s_waitcnt vmcnt(8)
	s_waitcnt lgkmcnt(0)
	s_barrier
	s_setprio 1
	s_waitcnt lgkmcnt(0)
	v_mfma_f32_16x16x32_bf16 v[64:67], v[112:115], v[164:167], v[64:67]
	v_mfma_f32_16x16x32_bf16 v[60:63], v[124:127], v[164:167], v[60:63]
	s_waitcnt lgkmcnt(5)
	v_mfma_f32_16x16x32_bf16 v[48:51], v[112:115], v[178:181], v[48:51]
	v_mfma_f32_16x16x32_bf16 v[44:47], v[124:127], v[178:181], v[44:47]
	s_waitcnt lgkmcnt(3)
	v_mfma_f32_16x16x32_bf16 v[32:35], v[112:115], v[194:197], v[32:35]
	v_mfma_f32_16x16x32_bf16 v[28:31], v[124:127], v[194:197], v[28:31]
	s_waitcnt lgkmcnt(1)
	v_mfma_f32_16x16x32_bf16 v[16:19], v[112:115], v[202:205], v[16:19]
	v_mfma_f32_16x16x32_bf16 v[12:15], v[124:127], v[202:205], v[12:15]
	v_mfma_f32_16x16x32_bf16 v[64:67], v[120:123], v[168:171], v[64:67]
	v_mfma_f32_16x16x32_bf16 v[60:63], v[132:135], v[168:171], v[60:63]
	v_mfma_f32_16x16x32_bf16 v[48:51], v[120:123], v[190:193], v[48:51]
	v_mfma_f32_16x16x32_bf16 v[44:47], v[132:135], v[190:193], v[44:47]
	v_mfma_f32_16x16x32_bf16 v[32:35], v[120:123], v[198:201], v[32:35]
	v_mfma_f32_16x16x32_bf16 v[28:31], v[132:135], v[198:201], v[28:31]
	s_waitcnt lgkmcnt(0)
	v_mfma_f32_16x16x32_bf16 v[16:19], v[120:123], v[206:209], v[16:19]
	v_mfma_f32_16x16x32_bf16 v[12:15], v[132:135], v[206:209], v[12:15]
	s_setprio 0
	s_setprio 1
	v_mfma_f32_16x16x32_bf16 v[56:59], v[148:151], v[164:167], v[56:59]
	v_mfma_f32_16x16x32_bf16 v[52:55], v[156:159], v[164:167], v[52:55]
	v_mfma_f32_16x16x32_bf16 v[40:43], v[148:151], v[178:181], v[40:43]
	v_mfma_f32_16x16x32_bf16 v[36:39], v[156:159], v[178:181], v[36:39]
	v_mfma_f32_16x16x32_bf16 v[24:27], v[148:151], v[194:197], v[24:27]
	v_mfma_f32_16x16x32_bf16 v[20:23], v[156:159], v[194:197], v[20:23]
	v_mfma_f32_16x16x32_bf16 v[8:11], v[148:151], v[202:205], v[8:11]
	v_mfma_f32_16x16x32_bf16 v[2:5], v[156:159], v[202:205], v[4:7]
	v_mfma_f32_16x16x32_bf16 v[56:59], v[152:155], v[168:171], v[56:59]
	v_mfma_f32_16x16x32_bf16 v[52:55], v[160:163], v[168:171], v[52:55]
	v_mfma_f32_16x16x32_bf16 v[40:43], v[152:155], v[190:193], v[40:43]
	v_mfma_f32_16x16x32_bf16 v[36:39], v[160:163], v[190:193], v[36:39]
	v_mfma_f32_16x16x32_bf16 v[24:27], v[152:155], v[198:201], v[24:27]
	v_mfma_f32_16x16x32_bf16 v[20:23], v[160:163], v[198:201], v[20:23]
	v_mfma_f32_16x16x32_bf16 v[8:11], v[152:155], v[206:209], v[8:11]
	v_mfma_f32_16x16x32_bf16 v[2:5], v[160:163], v[206:209], v[2:5]
	s_setprio 0
	s_barrier
	v_add_u32_e32 v189, 0x18000, v186
	v_add_u32_e32 v190, 0x1c000, v186
	ds_read_b128 v[112:115], v189
	ds_read_b128 v[120:123], v189 offset:1024
	ds_read_b128 v[124:127], v189 offset:2048
	ds_read_b128 v[132:135], v189 offset:3072
	ds_read_b128 v[148:151], v190
	ds_read_b128 v[152:155], v190 offset:1024
	ds_read_b128 v[156:159], v190 offset:2048
	ds_read_b128 v[160:163], v190 offset:3072
	ds_read_b128 v[164:167], v187 offset:32768
	ds_read_b128 v[168:171], v187 offset:33792
	ds_read_b128 v[178:181], v187 offset:34816
	ds_read_b128 v[192:195], v187 offset:35840
	ds_read_b128 v[196:199], v187 offset:36864
	ds_read_b128 v[200:203], v187 offset:37888
	ds_read_b128 v[204:207], v187 offset:38912
	ds_read_b128 v[208:211], v187 offset:39936
	s_add_u32 s18, s18, 0x160000
	s_addc_u32 s19, s19, 0
	s_mov_b32 m0, s29
	s_nop 0
	global_load_lds_dwordx4 v174, s[18:19]
	s_nop 0
	s_mov_b32 m0, s30
	s_nop 0
	global_load_lds_dwordx4 v176, s[18:19]
	s_waitcnt vmcnt(8)
	s_waitcnt lgkmcnt(0)
	s_barrier
	s_setprio 1
	s_waitcnt lgkmcnt(0)
	v_mfma_f32_16x16x32_bf16 v[144:147], v[112:115], v[164:167], v[144:147]
	v_mfma_f32_16x16x32_bf16 v[140:143], v[124:127], v[164:167], v[140:143]
	s_waitcnt lgkmcnt(5)
	v_mfma_f32_16x16x32_bf16 v[116:119], v[112:115], v[178:181], v[116:119]
	v_mfma_f32_16x16x32_bf16 v[108:111], v[124:127], v[178:181], v[108:111]
	s_waitcnt lgkmcnt(3)
	v_mfma_f32_16x16x32_bf16 v[96:99], v[112:115], v[196:199], v[96:99]
	v_mfma_f32_16x16x32_bf16 v[92:95], v[124:127], v[196:199], v[92:95]
	s_waitcnt lgkmcnt(1)
	v_mfma_f32_16x16x32_bf16 v[80:83], v[112:115], v[204:207], v[80:83]
	v_mfma_f32_16x16x32_bf16 v[76:79], v[124:127], v[204:207], v[76:79]
	v_mfma_f32_16x16x32_bf16 v[144:147], v[120:123], v[168:171], v[144:147]
	v_mfma_f32_16x16x32_bf16 v[140:143], v[132:135], v[168:171], v[140:143]
	v_mfma_f32_16x16x32_bf16 v[116:119], v[120:123], v[192:195], v[116:119]
	v_mfma_f32_16x16x32_bf16 v[108:111], v[132:135], v[192:195], v[108:111]
	v_mfma_f32_16x16x32_bf16 v[96:99], v[120:123], v[200:203], v[96:99]
	v_mfma_f32_16x16x32_bf16 v[92:95], v[132:135], v[200:203], v[92:95]
	s_waitcnt lgkmcnt(0)
	v_mfma_f32_16x16x32_bf16 v[80:83], v[120:123], v[208:211], v[80:83]
	v_mfma_f32_16x16x32_bf16 v[76:79], v[132:135], v[208:211], v[76:79]
	s_setprio 0
	s_setprio 1
	v_mfma_f32_16x16x32_bf16 v[136:139], v[148:151], v[164:167], v[136:139]
	v_mfma_f32_16x16x32_bf16 v[128:131], v[156:159], v[164:167], v[128:131]
	v_mfma_f32_16x16x32_bf16 v[104:107], v[148:151], v[178:181], v[104:107]
	v_mfma_f32_16x16x32_bf16 v[100:103], v[156:159], v[178:181], v[100:103]
	v_mfma_f32_16x16x32_bf16 v[88:91], v[148:151], v[196:199], v[88:91]
	v_mfma_f32_16x16x32_bf16 v[84:87], v[156:159], v[196:199], v[84:87]
	v_mfma_f32_16x16x32_bf16 v[72:75], v[148:151], v[204:207], v[72:75]
	v_mfma_f32_16x16x32_bf16 v[68:71], v[156:159], v[204:207], v[68:71]
	v_mfma_f32_16x16x32_bf16 v[136:139], v[152:155], v[168:171], v[136:139]
	v_mfma_f32_16x16x32_bf16 v[128:131], v[160:163], v[168:171], v[128:131]
	v_mfma_f32_16x16x32_bf16 v[104:107], v[152:155], v[192:195], v[104:107]
	v_mfma_f32_16x16x32_bf16 v[100:103], v[160:163], v[192:195], v[100:103]
	v_mfma_f32_16x16x32_bf16 v[88:91], v[152:155], v[200:203], v[88:91]
	v_mfma_f32_16x16x32_bf16 v[84:87], v[160:163], v[200:203], v[84:87]
	v_mfma_f32_16x16x32_bf16 v[72:75], v[152:155], v[208:211], v[72:75]
	v_mfma_f32_16x16x32_bf16 v[68:71], v[160:163], v[208:211], v[68:71]
	s_setprio 0
	s_barrier
;     __device__ __forceinline__ void operator()(const f32x4 (&acc)[2][2][4][2], const Unit& u, int wr, int wc, int fr, int fq) const {
;         const int row0 = u.pm * BM + wr * 64 + fr, col0 = u.pn * BM + wc * 32 + 8 * fq;
; template <class Epi, class Sched, bool ALIGN_EPI = false, bool SP2 = false>
; __device__ __forceinline__ void gemm_phase(PG8_LAS unsigned char* lds, const Gemm g, const Sched& S, const Epi& E) {
;     ...
;         for (int t = (DRO && ui > 0) ? 2 : 0; t < nt; t += 2) {
;             const bool last = (t == nt - 2);
;             const char* a1 = cA + (size_t)(t + 1) * kstep;
;             const char* a2 = last ? nA : cA + (size_t)(t + 2) * kstep; const char* b2 = last ? nB : cB + (size_t)(t + 2) * kstep;
;             const char* a3 = a2 + kstep; const char* b3 = b2 + kstep;
;             if (last && has_next) S.a_ready(nxt);
;             if constexpr (SP2) {
;             PG8_TRIP(true, PG8_WAIT_V(8));
;             } else {
;             PG8_LDB(B0, 0, 0); PG8_SCHED; PG8_LDA(At, 0, 0); PG8_STAGE(PG8_SA(1, 1), a1 + hsA, voffA);
;             PG8_WAIT_L(8); PG8_BAR; PG8_WAIT_L(0); PG8_MMA(0, 0, At, B0); PG8_BAR; PG8_SCHED;
;             PG8_LDB(B1, 0, 1); PG8_STAGE(PG8_SB(0, 0), b2, voffB);
;             PG8_BAR; PG8_WAIT_L(0); PG8_MMA(0, 1, At, B1); PG8_BAR;
;             PG8_LDA(At, 0, 1); PG8_STAGE(PG8_SA(0, 0), a2, voffA);
;             PG8_BAR; PG8_WAIT_L(0); PG8_MMA(1, 0, At, B0); PG8_BAR; PG8_SCHED;
;             PG8_STAGE(PG8_SB(0, 1), b2 + hsB, voffB);
;             PG8_WAIT_V(6); PG8_BAR; PG8_MMA(1, 1, At, B1); PG8_BAR;
;             PG8_LDB(B0, 1, 0); PG8_SCHED; PG8_LDA(At, 1, 0); PG8_STAGE(PG8_SA(0, 1), a2 + hsA, voffA);
;             PG8_WAIT_L(8); PG8_BAR; PG8_WAIT_L(0); PG8_MMA(0, 0, At, B0); PG8_BAR; PG8_SCHED;
;             PG8_LDB(B1, 1, 1); PG8_STAGE(PG8_SB(1, 0), b3, voffB);
;             PG8_BAR; PG8_WAIT_L(0); PG8_MMA(0, 1, At, B1); PG8_BAR;
;             PG8_LDA(At, 1, 1); PG8_STAGE(PG8_SA(1, 0), a3, voffA);
;             PG8_BAR; PG8_WAIT_L(0); PG8_MMA(1, 0, At, B0); PG8_BAR; PG8_SCHED;
;             PG8_STAGE(PG8_SB(1, 1), b3 + hsB, voffB);
;             PG8_WAIT_V(6); PG8_BAR; PG8_MMA(1, 1, At, B1); PG8_BAR;
;             }
;         }
;         if constexpr (DRO) { asm volatile("" ::: "memory"); PG8_STAGE(PG8_SA(1, 1), nA + kstep + hsA, voffA); asm volatile("" ::: "memory"); }
	ds_read_b128 v[164:167], v187 offset:49152
	ds_read_b128 v[168:171], v187 offset:50176
	ds_read_b128 v[178:181], v187 offset:51200
	ds_read_b128 v[192:195], v187 offset:52224
	ds_read_b128 v[196:199], v187 offset:53248
	ds_read_b128 v[200:203], v187 offset:54272
	ds_read_b128 v[204:207], v187 offset:55296
	ds_read_b128 v[208:211], v187 offset:56320
	s_add_u32 s18, s16, 0x80
	s_addc_u32 s19, s17, 0
	s_mov_b32 m0, s34
	s_nop 0
	global_load_lds_dwordx4 v175, s[18:19]
	s_add_u32 s16, s16, 0x160080
	s_mov_b32 m0, s35
	s_nop 0
	global_load_lds_dwordx4 v177, s[18:19]
	s_addc_u32 s17, s17, 0
	s_mov_b32 m0, s40
	s_nop 0
	global_load_lds_dwordx4 v175, s[16:17]
	s_nop 0
	s_mov_b32 m0, s41
	s_nop 0
	global_load_lds_dwordx4 v177, s[16:17]
	s_nop 0
	s_mov_b32 m0, s36
	s_nop 0
	global_load_lds_dwordx4 v174, s[14:15]
	s_nop 0
	s_mov_b32 m0, s37
	s_nop 0
	global_load_lds_dwordx4 v176, s[14:15]
	s_waitcnt vmcnt(8)
	s_waitcnt lgkmcnt(0)
	s_barrier
	s_setprio 1
	s_waitcnt lgkmcnt(0)
	v_mfma_f32_16x16x32_bf16 v[64:67], v[112:115], v[164:167], v[64:67]
	v_mfma_f32_16x16x32_bf16 v[60:63], v[124:127], v[164:167], v[60:63]
	s_waitcnt lgkmcnt(5)
	v_mfma_f32_16x16x32_bf16 v[48:51], v[112:115], v[178:181], v[48:51]
	v_mfma_f32_16x16x32_bf16 v[44:47], v[124:127], v[178:181], v[44:47]
	s_waitcnt lgkmcnt(3)
	v_mfma_f32_16x16x32_bf16 v[32:35], v[112:115], v[196:199], v[32:35]
	v_mfma_f32_16x16x32_bf16 v[28:31], v[124:127], v[196:199], v[28:31]
	s_waitcnt lgkmcnt(1)
	v_mfma_f32_16x16x32_bf16 v[16:19], v[112:115], v[204:207], v[16:19]
	v_mfma_f32_16x16x32_bf16 v[12:15], v[124:127], v[204:207], v[12:15]
	v_mfma_f32_16x16x32_bf16 v[64:67], v[120:123], v[168:171], v[64:67]
	v_mfma_f32_16x16x32_bf16 v[60:63], v[132:135], v[168:171], v[60:63]
	v_mfma_f32_16x16x32_bf16 v[48:51], v[120:123], v[192:195], v[48:51]
	v_mfma_f32_16x16x32_bf16 v[44:47], v[132:135], v[192:195], v[44:47]
	v_mfma_f32_16x16x32_bf16 v[32:35], v[120:123], v[200:203], v[32:35]
	v_mfma_f32_16x16x32_bf16 v[28:31], v[132:135], v[200:203], v[28:31]
	s_waitcnt lgkmcnt(0)
	v_mfma_f32_16x16x32_bf16 v[16:19], v[120:123], v[208:211], v[16:19]
	v_mfma_f32_16x16x32_bf16 v[12:15], v[132:135], v[208:211], v[12:15]
	s_setprio 0
	s_setprio 1
	v_mfma_f32_16x16x32_bf16 v[56:59], v[148:151], v[164:167], v[56:59]
	v_mfma_f32_16x16x32_bf16 v[52:55], v[156:159], v[164:167], v[52:55]
	v_mfma_f32_16x16x32_bf16 v[40:43], v[148:151], v[178:181], v[40:43]
	v_mfma_f32_16x16x32_bf16 v[36:39], v[156:159], v[178:181], v[36:39]
	v_mfma_f32_16x16x32_bf16 v[24:27], v[148:151], v[196:199], v[24:27]
	v_mfma_f32_16x16x32_bf16 v[20:23], v[156:159], v[196:199], v[20:23]
	v_mfma_f32_16x16x32_bf16 v[6:9], v[148:151], v[204:207], v[8:11]
	v_mfma_f32_16x16x32_bf16 v[2:5], v[156:159], v[204:207], v[2:5]
	v_mfma_f32_16x16x32_bf16 v[56:59], v[152:155], v[168:171], v[56:59]
	v_mfma_f32_16x16x32_bf16 v[52:55], v[160:163], v[168:171], v[52:55]
	v_mfma_f32_16x16x32_bf16 v[40:43], v[152:155], v[192:195], v[40:43]
	v_mfma_f32_16x16x32_bf16 v[36:39], v[160:163], v[192:195], v[36:39]
	v_mfma_f32_16x16x32_bf16 v[24:27], v[152:155], v[200:203], v[24:27]
	v_mfma_f32_16x16x32_bf16 v[20:23], v[160:163], v[200:203], v[20:23]
	v_mfma_f32_16x16x32_bf16 v[8:11], v[152:155], v[208:211], v[6:9]
	v_mfma_f32_16x16x32_bf16 v[4:7], v[160:163], v[208:211], v[2:5]
	s_setprio 0
	s_barrier
	s_add_i32 s52, s52, 2
	s_add_u32 s53, s53, 0x100
	s_addc_u32 s57, s57, 0
	s_add_u32 s12, s12, 0x100
	s_addc_u32 s13, s13, 0
	s_cmpk_gt_u32 s52, 0x55
	s_cbranch_scc0 .LBB0_1226
	s_add_u32 s12, s8, 0x160080
	s_addc_u32 s13, s9, 0
	s_mov_b32 m0, s44
	s_nop 0
	global_load_lds_dwordx4 v174, s[12:13]
	v_lshl_add_u32 v2, s51, 8, v184
	s_mov_b32 m0, s45
	s_nop 0
	global_load_lds_dwordx4 v176, s[12:13]
	s_min_i32 s12, s51, 64
	s_ashr_i32 s12, s12, 4
	s_mul_hi_i32 s13, s12, 0xc000
	s_mul_i32 s12, s12, 0xc000
	v_ashrrev_i32_e32 v3, 31, v2
	v_lshl_or_b32 v148, s49, 8, v185
	s_add_u32 s12, s31, s12
	v_lshlrev_b64 v[2:3], 12, v[2:3]
	s_addc_u32 s13, s33, s13
	v_ashrrev_i32_e32 v149, 31, v148
	v_lshl_add_u64 v[2:3], s[80:81], 0, v[2:3]
	v_lshl_add_u64 v[112:113], v[148:149], 2, s[12:13]
	v_lshl_add_u64 v[2:3], v[148:149], 1, v[2:3]
	global_load_dwordx4 v[132:135], v[112:113], off
	global_load_dwordx4 v[124:127], v[112:113], off offset:16
	global_load_dwordx4 v[120:123], v[112:113], off offset:512
	global_load_dwordx4 v[112:115], v[112:113], off offset:528
	global_load_dwordx4 v[178:181], v[2:3], off
	global_load_dwordx4 v[192:195], v[2:3], off offset:256
	v_add_co_u32_e32 v172, vcc, 0x10000, v2
	s_nop 1
	v_addc_co_u32_e32 v173, vcc, 0, v3, vcc
	global_load_dwordx4 v[196:199], v[172:173], off
	global_load_dwordx4 v[164:167], v[172:173], off offset:256
	v_add_co_u32_e32 v170, vcc, 0x20000, v2
	s_nop 1
	v_addc_co_u32_e32 v171, vcc, 0, v3, vcc
	global_load_dwordx4 v[160:163], v[170:171], off
	global_load_dwordx4 v[156:159], v[170:171], off offset:256
	v_add_co_u32_e32 v168, vcc, 0x30000, v2
	s_nop 1
	v_addc_co_u32_e32 v169, vcc, 0, v3, vcc
	global_load_dwordx4 v[152:155], v[168:169], off
	global_load_dwordx4 v[148:151], v[168:169], off offset:256
	v_add_co_u32_e32 v244, vcc, 0x80000, v2
	s_nop 1
	v_addc_co_u32_e32 v245, vcc, 0, v3, vcc
	global_load_dwordx4 v[212:215], v[244:245], off
	global_load_dwordx4 v[216:219], v[244:245], off offset:256
	v_add_co_u32_e32 v246, vcc, 0x90000, v2
	s_nop 1
	v_addc_co_u32_e32 v247, vcc, 0, v3, vcc
	global_load_dwordx4 v[220:223], v[246:247], off
	global_load_dwordx4 v[224:227], v[246:247], off offset:256
	v_add_co_u32_e32 v248, vcc, 0xa0000, v2
	s_nop 1
	v_addc_co_u32_e32 v249, vcc, 0, v3, vcc
	global_load_dwordx4 v[228:231], v[248:249], off
	global_load_dwordx4 v[232:235], v[248:249], off offset:256
	v_add_co_u32_e32 v250, vcc, 0xb0000, v2
	s_nop 1
	v_addc_co_u32_e32 v251, vcc, 0, v3, vcc
	global_load_dwordx4 v[236:239], v[250:251], off
	global_load_dwordx4 v[240:243], v[250:251], off offset:256
	s_nop 0
	s_nop 0
	s_mov_b32 s12, 0x10000
	s_mov_b32 s12, 0x90000
	s_nop 0
	s_waitcnt vmcnt(15)
; #define ER_LOAD(dst, ai, mp) do { _Pragma("unroll") for (int mm = 0; mm < 2; ++mm) _Pragma("unroll") for (int bj = 0; bj < 2; ++bj) \
;             dst[mm][bj] = *(const u32x4*)(xb + (size_t)((ai) * HALF + (2 * (mp) + mm) * 16) * 2048 + bj * HALF); } while (0)
;     __device__ __forceinline__ void operator()(const f32x4 (&acc)[2][2][4][2], const Unit& u, int wr, int wc, int fr, int fq) const {
;     ...
;         ER_LOAD(xa, 0, 0); ER_LOAD(xc, 0, 1);
;         ER_STORE(xa, 0, 0); ER_LOAD(xa, 1, 0);
;         ER_STORE(xc, 0, 1); ER_LOAD(xc, 1, 1);
	v_cvt_f32_f16_e32 v200, v178
	v_cvt_f32_f16_sdwa v201, v178 dst_sel:DWORD dst_unused:UNUSED_PAD src0_sel:WORD_1
	s_nop 0
	v_cvt_f32_f16_e32 v178, v179
	v_cvt_f32_f16_sdwa v179, v179 dst_sel:DWORD dst_unused:UNUSED_PAD src0_sel:WORD_1
	v_pk_fma_f32 v[144:145], v[144:145], v[132:133], v[200:201]
	v_pk_fma_f32 v[146:147], v[146:147], v[134:135], v[178:179]
	v_cvt_f32_f16_e32 v178, v180
	v_cvt_f32_f16_sdwa v179, v180 dst_sel:DWORD dst_unused:UNUSED_PAD src0_sel:WORD_1
	v_cvt_f32_f16_e32 v180, v181
	v_cvt_f32_f16_sdwa v181, v181 dst_sel:DWORD dst_unused:UNUSED_PAD src0_sel:WORD_1
	v_pk_fma_f32 v[180:181], v[142:143], v[126:127], v[180:181]
	v_pk_fma_f32 v[142:143], v[140:141], v[124:125], v[178:179]
	v_cvt_pk_f16_f32 v140, v144, v145
	v_cvt_pk_f16_f32 v141, v146, v147
	v_cvt_pk_f16_f32 v142, v142, v143
	v_cvt_pk_f16_f32 v143, v180, v181
	global_store_dwordx4 v[2:3], v[140:143], off
	s_nop 1
	s_waitcnt vmcnt(15)
	v_cvt_f32_f16_e32 v140, v192
	v_cvt_f32_f16_sdwa v141, v192 dst_sel:DWORD dst_unused:UNUSED_PAD src0_sel:WORD_1
	v_cvt_f32_f16_e32 v142, v193
	v_cvt_f32_f16_sdwa v143, v193 dst_sel:DWORD dst_unused:UNUSED_PAD src0_sel:WORD_1
	v_pk_fma_f32 v[136:137], v[136:137], v[120:121], v[140:141]
	v_cvt_f32_f16_e32 v140, v194
	v_pk_fma_f32 v[138:139], v[138:139], v[122:123], v[142:143]
	v_cvt_f32_f16_sdwa v141, v194 dst_sel:DWORD dst_unused:UNUSED_PAD src0_sel:WORD_1
	v_cvt_f32_f16_e32 v142, v195
	v_cvt_f32_f16_sdwa v143, v195 dst_sel:DWORD dst_unused:UNUSED_PAD src0_sel:WORD_1
	v_pk_fma_f32 v[142:143], v[130:131], v[114:115], v[142:143]
	v_pk_fma_f32 v[130:131], v[128:129], v[112:113], v[140:141]
	v_cvt_pk_f16_f32 v128, v136, v137
	v_cvt_pk_f16_f32 v129, v138, v139
	v_cvt_pk_f16_f32 v130, v130, v131
	v_cvt_pk_f16_f32 v131, v142, v143
	global_store_dwordx4 v[2:3], v[128:131], off offset:256
	s_waitcnt vmcnt(13)
	v_cvt_f32_f16_e32 v136, v160
	v_cvt_f32_f16_e32 v128, v196
	v_cvt_f32_f16_sdwa v129, v196 dst_sel:DWORD dst_unused:UNUSED_PAD src0_sel:WORD_1
	v_cvt_f32_f16_e32 v130, v197
	v_cvt_f32_f16_sdwa v131, v197 dst_sel:DWORD dst_unused:UNUSED_PAD src0_sel:WORD_1
	v_cvt_f32_f16_sdwa v137, v160 dst_sel:DWORD dst_unused:UNUSED_PAD src0_sel:WORD_1
	v_pk_fma_f32 v[116:117], v[116:117], v[132:133], v[128:129]
	v_cvt_f32_f16_e32 v128, v198
	v_pk_fma_f32 v[118:119], v[118:119], v[134:135], v[130:131]
	v_cvt_f32_f16_sdwa v129, v198 dst_sel:DWORD dst_unused:UNUSED_PAD src0_sel:WORD_1
	v_cvt_f32_f16_e32 v130, v199
	v_cvt_f32_f16_sdwa v131, v199 dst_sel:DWORD dst_unused:UNUSED_PAD src0_sel:WORD_1
	v_cvt_f32_f16_e32 v138, v161
	v_cvt_f32_f16_sdwa v139, v161 dst_sel:DWORD dst_unused:UNUSED_PAD src0_sel:WORD_1
	v_pk_fma_f32 v[96:97], v[96:97], v[132:133], v[136:137]
	v_pk_fma_f32 v[130:131], v[110:111], v[126:127], v[130:131]
	v_pk_fma_f32 v[110:111], v[108:109], v[124:125], v[128:129]
	v_cvt_pk_f16_f32 v108, v116, v117
	v_cvt_pk_f16_f32 v109, v118, v119
	v_cvt_pk_f16_f32 v110, v110, v111
	v_cvt_pk_f16_f32 v111, v130, v131
	global_store_dwordx4 v[172:173], v[108:111], off
	v_add_co_u32_e32 v130, vcc, s83, v2
	s_nop 0
	v_cvt_f32_f16_e32 v108, v164
	v_cvt_f32_f16_sdwa v109, v164 dst_sel:DWORD dst_unused:UNUSED_PAD src0_sel:WORD_1
	v_cvt_f32_f16_e32 v110, v165
	v_cvt_f32_f16_sdwa v111, v165 dst_sel:DWORD dst_unused:UNUSED_PAD src0_sel:WORD_1
	v_addc_co_u32_e32 v131, vcc, 0, v3, vcc
	v_pk_fma_f32 v[104:105], v[104:105], v[120:121], v[108:109]
	v_pk_fma_f32 v[106:107], v[106:107], v[122:123], v[110:111]
	v_cvt_f32_f16_e32 v108, v166
	v_cvt_f32_f16_sdwa v109, v166 dst_sel:DWORD dst_unused:UNUSED_PAD src0_sel:WORD_1
	v_cvt_f32_f16_e32 v110, v167
	v_cvt_f32_f16_sdwa v111, v167 dst_sel:DWORD dst_unused:UNUSED_PAD src0_sel:WORD_1
	v_pk_fma_f32 v[98:99], v[98:99], v[134:135], v[138:139]
	v_cvt_f32_f16_e32 v136, v162
	v_cvt_f32_f16_sdwa v137, v162 dst_sel:DWORD dst_unused:UNUSED_PAD src0_sel:WORD_1
	v_pk_fma_f32 v[110:111], v[102:103], v[114:115], v[110:111]
	v_pk_fma_f32 v[102:103], v[100:101], v[112:113], v[108:109]
	v_cvt_pk_f16_f32 v100, v104, v105
	v_cvt_pk_f16_f32 v101, v106, v107
	v_cvt_pk_f16_f32 v102, v102, v103
	v_cvt_pk_f16_f32 v103, v110, v111
	global_store_dwordx4 v[172:173], v[100:103], off offset:256
	v_cvt_f32_f16_e32 v138, v163
	v_cvt_f32_f16_sdwa v139, v163 dst_sel:DWORD dst_unused:UNUSED_PAD src0_sel:WORD_1
	v_add_co_u32_e32 v128, vcc, s12, v2
	s_mov_b32 s12, 0xa0000
	v_pk_fma_f32 v[138:139], v[94:95], v[126:127], v[138:139]
	v_pk_fma_f32 v[94:95], v[92:93], v[124:125], v[136:137]
	v_addc_co_u32_e32 v129, vcc, 0, v3, vcc
	v_cvt_pk_f16_f32 v92, v96, v97
	v_cvt_pk_f16_f32 v93, v98, v99
	v_cvt_pk_f16_f32 v94, v94, v95
	v_cvt_pk_f16_f32 v95, v138, v139
	s_nop 0
	global_store_dwordx4 v[170:171], v[92:95], off
	s_nop 1
	s_waitcnt vmcnt(15)
	v_cvt_f32_f16_e32 v92, v156
	v_cvt_f32_f16_sdwa v93, v156 dst_sel:DWORD dst_unused:UNUSED_PAD src0_sel:WORD_1
	v_cvt_f32_f16_e32 v94, v157
	v_cvt_f32_f16_sdwa v95, v157 dst_sel:DWORD dst_unused:UNUSED_PAD src0_sel:WORD_1
	v_pk_fma_f32 v[88:89], v[88:89], v[120:121], v[92:93]
	v_cvt_f32_f16_e32 v92, v158
	v_pk_fma_f32 v[90:91], v[90:91], v[122:123], v[94:95]
	v_cvt_f32_f16_sdwa v93, v158 dst_sel:DWORD dst_unused:UNUSED_PAD src0_sel:WORD_1
	v_cvt_f32_f16_e32 v94, v159
	v_cvt_f32_f16_sdwa v95, v159 dst_sel:DWORD dst_unused:UNUSED_PAD src0_sel:WORD_1
	v_pk_fma_f32 v[94:95], v[86:87], v[114:115], v[94:95]
	v_pk_fma_f32 v[86:87], v[84:85], v[112:113], v[92:93]
	v_cvt_pk_f16_f32 v84, v88, v89
	v_cvt_pk_f16_f32 v85, v90, v91
	v_cvt_pk_f16_f32 v86, v86, v87
	v_cvt_pk_f16_f32 v87, v94, v95
	global_store_dwordx4 v[170:171], v[84:87], off offset:256
	s_waitcnt vmcnt(13)
; #define ER_LOAD(dst, ai, mp) do { _Pragma("unroll") for (int mm = 0; mm < 2; ++mm) _Pragma("unroll") for (int bj = 0; bj < 2; ++bj) \
;             dst[mm][bj] = *(const u32x4*)(xb + (size_t)((ai) * HALF + (2 * (mp) + mm) * 16) * 2048 + bj * HALF); } while (0)
;     __device__ __forceinline__ void operator()(const f32x4 (&acc)[2][2][4][2], const Unit& u, int wr, int wc, int fr, int fq) const {
;     ...
;         ER_LOAD(xa, 0, 0); ER_LOAD(xc, 0, 1);
;         ER_STORE(xa, 0, 0); ER_LOAD(xa, 1, 0);
;         ER_STORE(xc, 0, 1); ER_LOAD(xc, 1, 1);
;         ER_STORE(xa, 1, 0); ER_STORE(xc, 1, 1);
	v_cvt_f32_f16_e32 v88, v213
	v_cvt_f32_f16_e32 v84, v152
	v_cvt_f32_f16_sdwa v85, v152 dst_sel:DWORD dst_unused:UNUSED_PAD src0_sel:WORD_1
	v_cvt_f32_f16_e32 v86, v153
	v_cvt_f32_f16_sdwa v87, v153 dst_sel:DWORD dst_unused:UNUSED_PAD src0_sel:WORD_1
	v_cvt_f32_f16_sdwa v89, v213 dst_sel:DWORD dst_unused:UNUSED_PAD src0_sel:WORD_1
	v_pk_fma_f32 v[80:81], v[80:81], v[132:133], v[84:85]
	v_cvt_f32_f16_e32 v84, v154
	v_pk_fma_f32 v[82:83], v[82:83], v[134:135], v[86:87]
	v_cvt_f32_f16_sdwa v85, v154 dst_sel:DWORD dst_unused:UNUSED_PAD src0_sel:WORD_1
	v_cvt_f32_f16_e32 v86, v155
	v_cvt_f32_f16_sdwa v87, v155 dst_sel:DWORD dst_unused:UNUSED_PAD src0_sel:WORD_1
	v_pk_fma_f32 v[66:67], v[66:67], v[134:135], v[88:89]
	v_cvt_f32_f16_e32 v88, v215
	v_cvt_f32_f16_sdwa v89, v215 dst_sel:DWORD dst_unused:UNUSED_PAD src0_sel:WORD_1
	v_pk_fma_f32 v[86:87], v[78:79], v[126:127], v[86:87]
	v_pk_fma_f32 v[78:79], v[76:77], v[124:125], v[84:85]
	v_cvt_pk_f16_f32 v76, v80, v81
	v_cvt_pk_f16_f32 v77, v82, v83
	v_cvt_pk_f16_f32 v78, v78, v79
	v_cvt_pk_f16_f32 v79, v86, v87
	global_store_dwordx4 v[168:169], v[76:79], off
	v_add_co_u32_e32 v84, vcc, s12, v2
	s_nop 0
	v_cvt_f32_f16_e32 v76, v148
	v_cvt_f32_f16_sdwa v77, v148 dst_sel:DWORD dst_unused:UNUSED_PAD src0_sel:WORD_1
	v_cvt_f32_f16_e32 v78, v149
	v_cvt_f32_f16_sdwa v79, v149 dst_sel:DWORD dst_unused:UNUSED_PAD src0_sel:WORD_1
	v_addc_co_u32_e32 v85, vcc, 0, v3, vcc
	v_pk_fma_f32 v[72:73], v[72:73], v[120:121], v[76:77]
	v_pk_fma_f32 v[74:75], v[74:75], v[122:123], v[78:79]
	v_cvt_f32_f16_e32 v76, v150
	v_cvt_f32_f16_sdwa v77, v150 dst_sel:DWORD dst_unused:UNUSED_PAD src0_sel:WORD_1
	v_cvt_f32_f16_e32 v78, v151
	v_cvt_f32_f16_sdwa v79, v151 dst_sel:DWORD dst_unused:UNUSED_PAD src0_sel:WORD_1
	s_mov_b32 s12, 0xb0000
	v_add_co_u32_e32 v2, vcc, s12, v2
	v_pk_fma_f32 v[78:79], v[70:71], v[114:115], v[78:79]
	v_pk_fma_f32 v[70:71], v[68:69], v[112:113], v[76:77]
	v_cvt_pk_f16_f32 v68, v72, v73
	v_cvt_pk_f16_f32 v69, v74, v75
	v_cvt_pk_f16_f32 v70, v70, v71
	v_cvt_pk_f16_f32 v71, v78, v79
	global_store_dwordx4 v[168:169], v[68:71], off offset:256
	v_addc_co_u32_e32 v3, vcc, 0, v3, vcc
	v_cvt_f32_f16_e32 v86, v212
	v_cvt_f32_f16_sdwa v87, v212 dst_sel:DWORD dst_unused:UNUSED_PAD src0_sel:WORD_1
	v_pk_fma_f32 v[88:89], v[62:63], v[126:127], v[88:89]
	s_mov_b64 s[12:13], -1
	s_and_b64 vcc, exec, s[10:11]
	v_pk_fma_f32 v[64:65], v[64:65], v[132:133], v[86:87]
	v_cvt_f32_f16_e32 v86, v214
	v_cvt_f32_f16_sdwa v87, v214 dst_sel:DWORD dst_unused:UNUSED_PAD src0_sel:WORD_1
	v_pk_fma_f32 v[62:63], v[60:61], v[124:125], v[86:87]
	v_cvt_pk_f16_f32 v60, v64, v65
	v_cvt_pk_f16_f32 v61, v66, v67
	v_cvt_pk_f16_f32 v62, v62, v63
	v_cvt_pk_f16_f32 v63, v88, v89
	global_store_dwordx4 v[130:131], v[60:63], off
	s_nop 1
	s_waitcnt vmcnt(15)
	v_cvt_f32_f16_e32 v60, v216
	v_cvt_f32_f16_sdwa v61, v216 dst_sel:DWORD dst_unused:UNUSED_PAD src0_sel:WORD_1
	v_cvt_f32_f16_e32 v62, v217
	v_cvt_f32_f16_sdwa v63, v217 dst_sel:DWORD dst_unused:UNUSED_PAD src0_sel:WORD_1
	v_pk_fma_f32 v[56:57], v[56:57], v[120:121], v[60:61]
	v_cvt_f32_f16_e32 v60, v218
	v_pk_fma_f32 v[58:59], v[58:59], v[122:123], v[62:63]
	v_cvt_f32_f16_sdwa v61, v218 dst_sel:DWORD dst_unused:UNUSED_PAD src0_sel:WORD_1
	v_cvt_f32_f16_e32 v62, v219
	v_cvt_f32_f16_sdwa v63, v219 dst_sel:DWORD dst_unused:UNUSED_PAD src0_sel:WORD_1
	v_pk_fma_f32 v[62:63], v[54:55], v[114:115], v[62:63]
	v_pk_fma_f32 v[54:55], v[52:53], v[112:113], v[60:61]
	v_cvt_pk_f16_f32 v52, v56, v57
	v_cvt_pk_f16_f32 v53, v58, v59
	v_cvt_pk_f16_f32 v54, v54, v55
	v_cvt_pk_f16_f32 v55, v62, v63
	global_store_dwordx4 v[130:131], v[52:55], off offset:256
	s_nop 1
	s_waitcnt vmcnt(15)
	v_cvt_f32_f16_e32 v52, v220
	v_cvt_f32_f16_sdwa v53, v220 dst_sel:DWORD dst_unused:UNUSED_PAD src0_sel:WORD_1
	v_cvt_f32_f16_e32 v54, v221
	v_cvt_f32_f16_sdwa v55, v221 dst_sel:DWORD dst_unused:UNUSED_PAD src0_sel:WORD_1
	v_pk_fma_f32 v[48:49], v[48:49], v[132:133], v[52:53]
	v_cvt_f32_f16_e32 v52, v222
	v_pk_fma_f32 v[50:51], v[50:51], v[134:135], v[54:55]
	v_cvt_f32_f16_sdwa v53, v222 dst_sel:DWORD dst_unused:UNUSED_PAD src0_sel:WORD_1
	v_cvt_f32_f16_e32 v54, v223
	v_cvt_f32_f16_sdwa v55, v223 dst_sel:DWORD dst_unused:UNUSED_PAD src0_sel:WORD_1
	v_pk_fma_f32 v[54:55], v[46:47], v[126:127], v[54:55]
	v_pk_fma_f32 v[46:47], v[44:45], v[124:125], v[52:53]
	v_cvt_pk_f16_f32 v44, v48, v49
	v_cvt_pk_f16_f32 v45, v50, v51
	v_cvt_pk_f16_f32 v46, v46, v47
	v_cvt_pk_f16_f32 v47, v54, v55
	global_store_dwordx4 v[128:129], v[44:47], off
	s_nop 1
	s_waitcnt vmcnt(15)
	v_cvt_f32_f16_e32 v44, v224
	v_cvt_f32_f16_sdwa v45, v224 dst_sel:DWORD dst_unused:UNUSED_PAD src0_sel:WORD_1
	v_cvt_f32_f16_e32 v46, v225
	v_cvt_f32_f16_sdwa v47, v225 dst_sel:DWORD dst_unused:UNUSED_PAD src0_sel:WORD_1
	v_pk_fma_f32 v[40:41], v[40:41], v[120:121], v[44:45]
	v_cvt_f32_f16_e32 v44, v226
	v_pk_fma_f32 v[42:43], v[42:43], v[122:123], v[46:47]
	v_cvt_f32_f16_sdwa v45, v226 dst_sel:DWORD dst_unused:UNUSED_PAD src0_sel:WORD_1
	v_cvt_f32_f16_e32 v46, v227
	v_cvt_f32_f16_sdwa v47, v227 dst_sel:DWORD dst_unused:UNUSED_PAD src0_sel:WORD_1
	v_pk_fma_f32 v[46:47], v[38:39], v[114:115], v[46:47]
	v_pk_fma_f32 v[38:39], v[36:37], v[112:113], v[44:45]
	v_cvt_pk_f16_f32 v36, v40, v41
	v_cvt_pk_f16_f32 v37, v42, v43
	v_cvt_pk_f16_f32 v38, v38, v39
	v_cvt_pk_f16_f32 v39, v46, v47
	global_store_dwordx4 v[128:129], v[36:39], off offset:256
	s_nop 0
	s_waitcnt vmcnt(15)
; #define ER_LOAD(dst, ai, mp) do { _Pragma("unroll") for (int mm = 0; mm < 2; ++mm) _Pragma("unroll") for (int bj = 0; bj < 2; ++bj) \
;             dst[mm][bj] = *(const u32x4*)(xb + (size_t)((ai) * HALF + (2 * (mp) + mm) * 16) * 2048 + bj * HALF); } while (0)
;     __device__ __forceinline__ void operator()(const f32x4 (&acc)[2][2][4][2], const Unit& u, int wr, int wc, int fr, int fq) const {
;     ...
;         ER_LOAD(xa, 0, 0); ER_LOAD(xc, 0, 1);
;         ER_STORE(xa, 0, 0); ER_LOAD(xa, 1, 0);
;         ER_STORE(xc, 0, 1); ER_LOAD(xc, 1, 1);
;         ER_STORE(xa, 1, 0); ER_STORE(xc, 1, 1);
	v_cvt_f32_f16_e32 v36, v228
	v_cvt_f32_f16_sdwa v37, v228 dst_sel:DWORD dst_unused:UNUSED_PAD src0_sel:WORD_1
	v_cvt_f32_f16_e32 v38, v229
	v_cvt_f32_f16_sdwa v39, v229 dst_sel:DWORD dst_unused:UNUSED_PAD src0_sel:WORD_1
	v_pk_fma_f32 v[32:33], v[32:33], v[132:133], v[36:37]
	v_cvt_f32_f16_e32 v36, v230
	v_pk_fma_f32 v[34:35], v[34:35], v[134:135], v[38:39]
	v_cvt_f32_f16_sdwa v37, v230 dst_sel:DWORD dst_unused:UNUSED_PAD src0_sel:WORD_1
	v_cvt_f32_f16_e32 v38, v231
	v_cvt_f32_f16_sdwa v39, v231 dst_sel:DWORD dst_unused:UNUSED_PAD src0_sel:WORD_1
	v_pk_fma_f32 v[38:39], v[30:31], v[126:127], v[38:39]
	v_pk_fma_f32 v[30:31], v[28:29], v[124:125], v[36:37]
	v_cvt_pk_f16_f32 v28, v32, v33
	v_cvt_pk_f16_f32 v29, v34, v35
	v_cvt_pk_f16_f32 v30, v30, v31
	v_cvt_pk_f16_f32 v31, v38, v39
	global_store_dwordx4 v[84:85], v[28:31], off
	s_nop 1
	s_waitcnt vmcnt(15)
	v_cvt_f32_f16_e32 v28, v232
	v_cvt_f32_f16_sdwa v29, v232 dst_sel:DWORD dst_unused:UNUSED_PAD src0_sel:WORD_1
	v_cvt_f32_f16_e32 v30, v233
	v_cvt_f32_f16_sdwa v31, v233 dst_sel:DWORD dst_unused:UNUSED_PAD src0_sel:WORD_1
	v_pk_fma_f32 v[24:25], v[24:25], v[120:121], v[28:29]
	v_cvt_f32_f16_e32 v28, v234
	v_pk_fma_f32 v[26:27], v[26:27], v[122:123], v[30:31]
	v_cvt_f32_f16_sdwa v29, v234 dst_sel:DWORD dst_unused:UNUSED_PAD src0_sel:WORD_1
	v_cvt_f32_f16_e32 v30, v235
	v_cvt_f32_f16_sdwa v31, v235 dst_sel:DWORD dst_unused:UNUSED_PAD src0_sel:WORD_1
	v_pk_fma_f32 v[30:31], v[22:23], v[114:115], v[30:31]
	v_pk_fma_f32 v[22:23], v[20:21], v[112:113], v[28:29]
	v_cvt_pk_f16_f32 v20, v24, v25
	v_cvt_pk_f16_f32 v21, v26, v27
	v_cvt_pk_f16_f32 v22, v22, v23
	v_cvt_pk_f16_f32 v23, v30, v31
	global_store_dwordx4 v[84:85], v[20:23], off offset:256
	s_nop 1
	s_waitcnt vmcnt(15)
	v_cvt_f32_f16_e32 v20, v236
	v_cvt_f32_f16_sdwa v21, v236 dst_sel:DWORD dst_unused:UNUSED_PAD src0_sel:WORD_1
	v_cvt_f32_f16_e32 v22, v237
	v_cvt_f32_f16_sdwa v23, v237 dst_sel:DWORD dst_unused:UNUSED_PAD src0_sel:WORD_1
	v_pk_fma_f32 v[16:17], v[16:17], v[132:133], v[20:21]
	v_cvt_f32_f16_e32 v20, v238
	v_pk_fma_f32 v[18:19], v[18:19], v[134:135], v[22:23]
	v_cvt_f32_f16_sdwa v21, v238 dst_sel:DWORD dst_unused:UNUSED_PAD src0_sel:WORD_1
	v_cvt_f32_f16_e32 v22, v239
	v_cvt_f32_f16_sdwa v23, v239 dst_sel:DWORD dst_unused:UNUSED_PAD src0_sel:WORD_1
	v_pk_fma_f32 v[22:23], v[14:15], v[126:127], v[22:23]
	v_pk_fma_f32 v[14:15], v[12:13], v[124:125], v[20:21]
	v_cvt_pk_f16_f32 v12, v16, v17
	v_cvt_pk_f16_f32 v13, v18, v19
	v_cvt_pk_f16_f32 v14, v14, v15
	v_cvt_pk_f16_f32 v15, v22, v23
	global_store_dwordx4 v[2:3], v[12:15], off
	s_nop 1
	s_waitcnt vmcnt(15)
	v_cvt_f32_f16_e32 v12, v240
	v_cvt_f32_f16_sdwa v13, v240 dst_sel:DWORD dst_unused:UNUSED_PAD src0_sel:WORD_1
	v_cvt_f32_f16_e32 v14, v241
	v_cvt_f32_f16_sdwa v15, v241 dst_sel:DWORD dst_unused:UNUSED_PAD src0_sel:WORD_1
	v_pk_fma_f32 v[8:9], v[8:9], v[120:121], v[12:13]
	v_cvt_f32_f16_e32 v12, v242
	v_pk_fma_f32 v[10:11], v[10:11], v[122:123], v[14:15]
	v_cvt_f32_f16_sdwa v13, v242 dst_sel:DWORD dst_unused:UNUSED_PAD src0_sel:WORD_1
	v_cvt_f32_f16_e32 v14, v243
	v_cvt_f32_f16_sdwa v15, v243 dst_sel:DWORD dst_unused:UNUSED_PAD src0_sel:WORD_1
	v_pk_fma_f32 v[14:15], v[6:7], v[114:115], v[14:15]
	v_pk_fma_f32 v[6:7], v[4:5], v[112:113], v[12:13]
	v_cvt_pk_f16_f32 v4, v8, v9
	v_cvt_pk_f16_f32 v5, v10, v11
	v_cvt_pk_f16_f32 v6, v6, v7
	v_cvt_pk_f16_f32 v7, v14, v15
	global_store_dwordx4 v[2:3], v[4:7], off offset:256
	s_cbranch_vccz .LBB0_1209
	ds_read_b128 v[2:5], v0
	ds_read_b128 v[6:9], v0 offset:1024
	ds_read_b128 v[10:13], v0 offset:2048
	ds_read_b128 v[14:17], v0 offset:3072
	ds_read_b128 v[18:21], v188
	ds_read_b128 v[22:25], v188 offset:1024
	ds_read_b128 v[26:29], v188 offset:2048
	ds_read_b128 v[30:33], v188 offset:3072
	s_add_u32 s12, s8, 0x100
	s_addc_u32 s13, s9, 0
	s_add_u32 s10, s8, 0x180
	s_addc_u32 s11, s9, 0
	s_add_u32 s14, s6, 0x100
	s_addc_u32 s15, s7, 0
	ds_read_b128 v[34:37], v187
	ds_read_b128 v[38:41], v187 offset:1024
	ds_read_b128 v[42:45], v187 offset:2048
	ds_read_b128 v[46:49], v187 offset:3072
	ds_read_b128 v[50:53], v187 offset:4096
	ds_read_b128 v[54:57], v187 offset:5120
	ds_read_b128 v[58:61], v187 offset:6144
	ds_read_b128 v[62:65], v187 offset:7168
	s_waitcnt vmcnt(44)
	s_waitcnt lgkmcnt(0)
	s_barrier
	s_setprio 1
	s_waitcnt lgkmcnt(0)
	v_mfma_f32_16x16x32_bf16 v[90:93], v[2:5], v[58:61], 0
	v_mfma_f32_16x16x32_bf16 v[66:69], v[2:5], v[34:37], 0
	v_mfma_f32_16x16x32_bf16 v[70:73], v[10:13], v[34:37], 0
	v_mfma_f32_16x16x32_bf16 v[74:77], v[2:5], v[42:45], 0
	v_mfma_f32_16x16x32_bf16 v[78:81], v[10:13], v[42:45], 0
	v_mfma_f32_16x16x32_bf16 v[82:85], v[2:5], v[50:53], 0
	v_mfma_f32_16x16x32_bf16 v[86:89], v[10:13], v[50:53], 0
	v_mfma_f32_16x16x32_bf16 v[100:103], v[6:9], v[62:65], v[90:93]
	v_mfma_f32_16x16x32_bf16 v[90:93], v[10:13], v[58:61], 0
	v_mfma_f32_16x16x32_bf16 v[66:69], v[6:9], v[38:41], v[66:69]
	v_mfma_f32_16x16x32_bf16 v[70:73], v[14:17], v[38:41], v[70:73]
	v_mfma_f32_16x16x32_bf16 v[74:77], v[6:9], v[46:49], v[74:77]
	v_mfma_f32_16x16x32_bf16 v[78:81], v[14:17], v[46:49], v[78:81]
	v_mfma_f32_16x16x32_bf16 v[82:85], v[6:9], v[54:57], v[82:85]
	v_mfma_f32_16x16x32_bf16 v[86:89], v[14:17], v[54:57], v[86:89]
	v_mfma_f32_16x16x32_bf16 v[104:107], v[14:17], v[62:65], v[90:93]
	s_setprio 0
	s_setprio 1
	v_mfma_f32_16x16x32_bf16 v[90:93], v[18:21], v[34:37], 0
	v_mfma_f32_16x16x32_bf16 v[34:37], v[26:29], v[34:37], 0
	v_mfma_f32_16x16x32_bf16 v[112:115], v[22:25], v[38:41], v[90:93]
	v_mfma_f32_16x16x32_bf16 v[34:37], v[30:33], v[38:41], v[34:37]
	v_mfma_f32_16x16x32_bf16 v[38:41], v[18:21], v[42:45], 0
	v_mfma_f32_16x16x32_bf16 v[42:45], v[26:29], v[42:45], 0
	v_mfma_f32_16x16x32_bf16 v[38:41], v[22:25], v[46:49], v[38:41]
	v_mfma_f32_16x16x32_bf16 v[42:45], v[30:33], v[46:49], v[42:45]
	v_mfma_f32_16x16x32_bf16 v[46:49], v[18:21], v[50:53], 0
	v_mfma_f32_16x16x32_bf16 v[50:53], v[26:29], v[50:53], 0
	v_mfma_f32_16x16x32_bf16 v[46:49], v[22:25], v[54:57], v[46:49]
	v_mfma_f32_16x16x32_bf16 v[50:53], v[30:33], v[54:57], v[50:53]
	v_mfma_f32_16x16x32_bf16 v[54:57], v[18:21], v[58:61], 0
	v_mfma_f32_16x16x32_bf16 v[58:61], v[26:29], v[58:61], 0
	v_mfma_f32_16x16x32_bf16 v[54:57], v[22:25], v[62:65], v[54:57]
	v_mfma_f32_16x16x32_bf16 v[58:61], v[30:33], v[62:65], v[58:61]
	s_setprio 0
	s_barrier
	ds_read_b128 v[62:65], v187 offset:16384
	ds_read_b128 v[90:93], v187 offset:17408
	ds_read_b128 v[94:97], v187 offset:18432
	ds_read_b128 v[108:111], v187 offset:19456
	ds_read_b128 v[116:119], v187 offset:20480
	ds_read_b128 v[120:123], v187 offset:21504
	ds_read_b128 v[124:127], v187 offset:22528
	ds_read_b128 v[128:131], v187 offset:23552
	s_mov_b32 m0, s22
	s_nop 0
	global_load_lds_dwordx4 v175, s[14:15]
	s_nop 0
	s_mov_b32 m0, s23
	s_nop 0
	global_load_lds_dwordx4 v177, s[14:15]
	s_add_u32 s14, s6, 0x160100
	s_addc_u32 s15, s7, 0
	s_mov_b32 m0, s26
	s_nop 0
	global_load_lds_dwordx4 v175, s[14:15]
	s_nop 0
	s_mov_b32 m0, s27
	s_nop 0
	global_load_lds_dwordx4 v177, s[14:15]
	s_nop 0
	s_mov_b32 m0, s21
	s_nop 0
	global_load_lds_dwordx4 v174, s[12:13]
	s_nop 0
	s_mov_b32 m0, s28
	s_nop 0
	global_load_lds_dwordx4 v176, s[12:13]
	s_waitcnt vmcnt(44)
	s_waitcnt lgkmcnt(0)
	s_barrier
	s_setprio 1
	s_waitcnt lgkmcnt(0)
	v_mfma_f32_16x16x32_bf16 v[136:139], v[10:13], v[62:65], 0
	v_mfma_f32_16x16x32_bf16 v[148:151], v[14:17], v[90:93], v[136:139]
	v_mfma_f32_16x16x32_bf16 v[136:139], v[2:5], v[94:97], 0
	v_mfma_f32_16x16x32_bf16 v[152:155], v[6:9], v[108:111], v[136:139]
	v_mfma_f32_16x16x32_bf16 v[136:139], v[10:13], v[94:97], 0
	v_mfma_f32_16x16x32_bf16 v[132:135], v[2:5], v[62:65], 0
	v_mfma_f32_16x16x32_bf16 v[156:159], v[14:17], v[108:111], v[136:139]
	v_mfma_f32_16x16x32_bf16 v[136:139], v[2:5], v[116:119], 0
	v_mfma_f32_16x16x32_bf16 v[2:5], v[2:5], v[124:127], 0
	v_mfma_f32_16x16x32_bf16 v[132:135], v[6:9], v[90:93], v[132:135]
	v_mfma_f32_16x16x32_bf16 v[160:163], v[6:9], v[120:123], v[136:139]
	v_mfma_f32_16x16x32_bf16 v[2:5], v[6:9], v[128:131], v[2:5]
	v_mfma_f32_16x16x32_bf16 v[6:9], v[10:13], v[124:127], 0
	v_mfma_f32_16x16x32_bf16 v[136:139], v[10:13], v[116:119], 0
	v_mfma_f32_16x16x32_bf16 v[6:9], v[14:17], v[128:131], v[6:9]
	v_mfma_f32_16x16x32_bf16 v[164:167], v[14:17], v[120:123], v[136:139]
	s_setprio 0
	s_setprio 1
	v_mfma_f32_16x16x32_bf16 v[10:13], v[18:21], v[62:65], 0
	v_mfma_f32_16x16x32_bf16 v[168:171], v[22:25], v[90:93], v[10:13]
	v_mfma_f32_16x16x32_bf16 v[10:13], v[26:29], v[62:65], 0
	v_mfma_f32_16x16x32_bf16 v[178:181], v[30:33], v[90:93], v[10:13]
	v_mfma_f32_16x16x32_bf16 v[10:13], v[18:21], v[94:97], 0
	v_mfma_f32_16x16x32_bf16 v[192:195], v[22:25], v[108:111], v[10:13]
	v_mfma_f32_16x16x32_bf16 v[10:13], v[26:29], v[94:97], 0
	v_mfma_f32_16x16x32_bf16 v[196:199], v[30:33], v[108:111], v[10:13]
	v_mfma_f32_16x16x32_bf16 v[10:13], v[18:21], v[116:119], 0
	v_mfma_f32_16x16x32_bf16 v[200:203], v[22:25], v[120:123], v[10:13]
	v_mfma_f32_16x16x32_bf16 v[10:13], v[26:29], v[116:119], 0
	v_mfma_f32_16x16x32_bf16 v[120:123], v[30:33], v[120:123], v[10:13]
	v_mfma_f32_16x16x32_bf16 v[10:13], v[18:21], v[124:127], 0
	v_mfma_f32_16x16x32_bf16 v[204:207], v[22:25], v[128:131], v[10:13]
	v_mfma_f32_16x16x32_bf16 v[10:13], v[26:29], v[124:127], 0
	v_mfma_f32_16x16x32_bf16 v[124:127], v[30:33], v[128:131], v[10:13]
	s_setprio 0
	s_barrier
	s_nop 4
	ds_read_b128 v[10:13], v189
	ds_read_b128 v[14:17], v189 offset:1024
	ds_read_b128 v[20:23], v189 offset:2048
	ds_read_b128 v[24:27], v189 offset:3072
	ds_read_b128 v[208:211], v190
	ds_read_b128 v[212:215], v190 offset:1024
	ds_read_b128 v[216:219], v190 offset:2048
	ds_read_b128 v[188:191], v190 offset:3072
	ds_read_b128 v[28:31], v187 offset:32768
	ds_read_b128 v[62:65], v187 offset:33792
	ds_read_b128 v[220:223], v187 offset:34816
	ds_read_b128 v[224:227], v187 offset:35840
	ds_read_b128 v[228:231], v187 offset:36864
	ds_read_b128 v[232:235], v187 offset:37888
	ds_read_b128 v[236:239], v187 offset:38912
	ds_read_b128 v[240:243], v187 offset:39936
	s_add_u32 s12, s8, 0x160100
	s_addc_u32 s13, s9, 0
	s_mov_b32 m0, s29
	s_nop 0
	global_load_lds_dwordx4 v174, s[12:13]
	s_nop 0
	s_mov_b32 m0, s30
	s_nop 0
	global_load_lds_dwordx4 v176, s[12:13]
	s_waitcnt vmcnt(44)
	s_waitcnt lgkmcnt(0)
	s_barrier
	s_setprio 1
	s_waitcnt lgkmcnt(0)
	v_mfma_f32_16x16x32_bf16 v[66:69], v[10:13], v[28:31], v[66:69]
	v_mfma_f32_16x16x32_bf16 v[144:147], v[14:17], v[62:65], v[66:69]
	v_mfma_f32_16x16x32_bf16 v[66:69], v[20:23], v[28:31], v[70:73]
	v_mfma_f32_16x16x32_bf16 v[140:143], v[24:27], v[62:65], v[66:69]
	v_mfma_f32_16x16x32_bf16 v[66:69], v[10:13], v[220:223], v[74:77]
	v_mfma_f32_16x16x32_bf16 v[116:119], v[14:17], v[224:227], v[66:69]
	v_mfma_f32_16x16x32_bf16 v[66:69], v[20:23], v[220:223], v[78:81]
	v_mfma_f32_16x16x32_bf16 v[108:111], v[24:27], v[224:227], v[66:69]
	v_mfma_f32_16x16x32_bf16 v[66:69], v[10:13], v[228:231], v[82:85]
	v_mfma_f32_16x16x32_bf16 v[96:99], v[14:17], v[232:235], v[66:69]
	v_mfma_f32_16x16x32_bf16 v[66:69], v[20:23], v[228:231], v[86:89]
	v_mfma_f32_16x16x32_bf16 v[92:95], v[24:27], v[232:235], v[66:69]
	v_mfma_f32_16x16x32_bf16 v[66:69], v[10:13], v[236:239], v[100:103]
	v_mfma_f32_16x16x32_bf16 v[80:83], v[14:17], v[240:243], v[66:69]
	v_mfma_f32_16x16x32_bf16 v[66:69], v[20:23], v[236:239], v[104:107]
	v_mfma_f32_16x16x32_bf16 v[76:79], v[24:27], v[240:243], v[66:69]
	s_setprio 0
	s_setprio 1
	v_mfma_f32_16x16x32_bf16 v[66:69], v[208:211], v[28:31], v[112:115]
	v_mfma_f32_16x16x32_bf16 v[28:31], v[216:219], v[28:31], v[34:37]
	v_mfma_f32_16x16x32_bf16 v[128:131], v[188:191], v[62:65], v[28:31]
	v_mfma_f32_16x16x32_bf16 v[28:31], v[208:211], v[220:223], v[38:41]
	v_mfma_f32_16x16x32_bf16 v[104:107], v[212:215], v[224:227], v[28:31]
	v_mfma_f32_16x16x32_bf16 v[28:31], v[216:219], v[220:223], v[42:45]
	v_mfma_f32_16x16x32_bf16 v[100:103], v[188:191], v[224:227], v[28:31]
	v_mfma_f32_16x16x32_bf16 v[28:31], v[208:211], v[228:231], v[46:49]
	v_mfma_f32_16x16x32_bf16 v[88:91], v[212:215], v[232:235], v[28:31]
	v_mfma_f32_16x16x32_bf16 v[28:31], v[216:219], v[228:231], v[50:53]
	v_mfma_f32_16x16x32_bf16 v[84:87], v[188:191], v[232:235], v[28:31]
	v_mfma_f32_16x16x32_bf16 v[28:31], v[208:211], v[236:239], v[54:57]
	v_mfma_f32_16x16x32_bf16 v[72:75], v[212:215], v[240:243], v[28:31]
	v_mfma_f32_16x16x32_bf16 v[28:31], v[216:219], v[236:239], v[58:61]
	v_mfma_f32_16x16x32_bf16 v[136:139], v[212:215], v[62:65], v[66:69]
	v_mfma_f32_16x16x32_bf16 v[68:71], v[188:191], v[240:243], v[28:31]
	s_setprio 0
	s_barrier
	ds_read_b128 v[36:39], v187 offset:49152
	ds_read_b128 v[40:43], v187 offset:50176
	ds_read_b128 v[112:115], v187 offset:51200
	ds_read_b128 v[220:223], v187 offset:52224
	ds_read_b128 v[224:227], v187 offset:53248
	ds_read_b128 v[228:231], v187 offset:54272
	ds_read_b128 v[232:235], v187 offset:55296
	ds_read_b128 v[236:239], v187 offset:56320
	s_add_u32 s12, s6, 0x180
	s_addc_u32 s13, s7, 0
	s_mov_b32 m0, s34
	s_nop 0
	global_load_lds_dwordx4 v175, s[12:13]
	s_nop 0
	s_mov_b32 m0, s35
	s_nop 0
	global_load_lds_dwordx4 v177, s[12:13]
	s_add_u32 s12, s6, 0x160180
	s_addc_u32 s13, s7, 0
	s_mov_b32 m0, s40
	s_nop 0
	global_load_lds_dwordx4 v175, s[12:13]
	s_nop 0
	s_mov_b32 m0, s41
	s_nop 0
	global_load_lds_dwordx4 v177, s[12:13]
	s_nop 0
	s_mov_b32 m0, s36
	s_nop 0
	global_load_lds_dwordx4 v174, s[10:11]
	s_nop 0
	s_mov_b32 m0, s37
	s_nop 0
	global_load_lds_dwordx4 v176, s[10:11]
	s_waitcnt vmcnt(8)
	s_waitcnt lgkmcnt(0)
	s_barrier
	s_setprio 1
	s_waitcnt lgkmcnt(0)
	v_mfma_f32_16x16x32_bf16 v[28:31], v[10:13], v[36:39], v[132:135]
	v_mfma_f32_16x16x32_bf16 v[64:67], v[14:17], v[40:43], v[28:31]
	v_mfma_f32_16x16x32_bf16 v[28:31], v[20:23], v[36:39], v[148:151]
	v_mfma_f32_16x16x32_bf16 v[60:63], v[24:27], v[40:43], v[28:31]
	v_mfma_f32_16x16x32_bf16 v[28:31], v[10:13], v[112:115], v[152:155]
	v_mfma_f32_16x16x32_bf16 v[48:51], v[14:17], v[220:223], v[28:31]
	v_mfma_f32_16x16x32_bf16 v[28:31], v[20:23], v[112:115], v[156:159]
	v_mfma_f32_16x16x32_bf16 v[44:47], v[24:27], v[220:223], v[28:31]
	v_mfma_f32_16x16x32_bf16 v[28:31], v[10:13], v[224:227], v[160:163]
	v_mfma_f32_16x16x32_bf16 v[2:5], v[10:13], v[232:235], v[2:5]
	v_mfma_f32_16x16x32_bf16 v[32:35], v[14:17], v[228:231], v[28:31]
	v_mfma_f32_16x16x32_bf16 v[28:31], v[20:23], v[224:227], v[164:167]
	v_mfma_f32_16x16x32_bf16 v[16:19], v[14:17], v[236:239], v[2:5]
	v_mfma_f32_16x16x32_bf16 v[2:5], v[20:23], v[232:235], v[6:9]
	v_mfma_f32_16x16x32_bf16 v[28:31], v[24:27], v[228:231], v[28:31]
	v_mfma_f32_16x16x32_bf16 v[12:15], v[24:27], v[236:239], v[2:5]
	s_setprio 0
	s_setprio 1
	v_mfma_f32_16x16x32_bf16 v[2:5], v[208:211], v[36:39], v[168:171]
	v_mfma_f32_16x16x32_bf16 v[56:59], v[212:215], v[40:43], v[2:5]
	v_mfma_f32_16x16x32_bf16 v[2:5], v[216:219], v[36:39], v[178:181]
	v_mfma_f32_16x16x32_bf16 v[52:55], v[188:191], v[40:43], v[2:5]
	v_mfma_f32_16x16x32_bf16 v[2:5], v[208:211], v[112:115], v[192:195]
	v_mfma_f32_16x16x32_bf16 v[40:43], v[212:215], v[220:223], v[2:5]
	v_mfma_f32_16x16x32_bf16 v[2:5], v[216:219], v[112:115], v[196:199]
	v_mfma_f32_16x16x32_bf16 v[36:39], v[188:191], v[220:223], v[2:5]
	v_mfma_f32_16x16x32_bf16 v[2:5], v[208:211], v[224:227], v[200:203]
	v_mfma_f32_16x16x32_bf16 v[24:27], v[212:215], v[228:231], v[2:5]
	v_mfma_f32_16x16x32_bf16 v[2:5], v[216:219], v[224:227], v[120:123]
	v_mfma_f32_16x16x32_bf16 v[20:23], v[188:191], v[228:231], v[2:5]
	v_mfma_f32_16x16x32_bf16 v[2:5], v[208:211], v[232:235], v[204:207]
	v_mfma_f32_16x16x32_bf16 v[8:11], v[212:215], v[236:239], v[2:5]
	v_mfma_f32_16x16x32_bf16 v[2:5], v[216:219], v[232:235], v[124:127]
	v_mfma_f32_16x16x32_bf16 v[4:7], v[188:191], v[236:239], v[2:5]
	s_setprio 0
	s_barrier
	s_mov_b64 s[12:13], 0
	s_branch .LBB0_1209
